# epilogue load hoists reworked: consumers read the hoisted registers directly (no register copies behind 128-bit stores), removed loads replaced by short pads
# baseline (speedup 1.0000x reference)
.LBB0_568:
	s_add_u32 s36, s28, 0xfffc0080
	s_addc_u32 s37, s29, -1
	s_add_i32 s68, s44, 0x120
	s_cmp_eq_u32 s67, 12
	s_cselect_b32 s39, s23, s37
	s_cselect_b32 s38, s61, s36
	v_add_u32_e32 v142, s68, v145
	s_cselect_b32 s37, s21, s66
	s_cselect_b32 s36, s62, s63
	s_add_i32 s70, s45, 0x120
	ds_read_b128 v[138:141], v142
	ds_read_b128 v[148:151], v142 offset:1024
	ds_read_b128 v[152:155], v142 offset:2048
	ds_read_b128 v[156:159], v142 offset:3072
	v_add_u32_e32 v142, s70, v145
	ds_read_b128 v[200:203], v142
	ds_read_b128 v[204:207], v142 offset:1024
	ds_read_b128 v[208:211], v142 offset:2048
	ds_read_b128 v[212:215], v142 offset:3072
	v_lshl_add_u64 v[142:143], s[28:29], 0, v[134:135]
	s_add_i32 m0, s52, 0xc000
	ds_read_b128 v[216:219], v147
	ds_read_b128 v[220:223], v147 offset:1024
	ds_read_b128 v[224:227], v147 offset:2048
	ds_read_b128 v[228:231], v147 offset:3072
	ds_read_b128 v[232:235], v147 offset:4096
	ds_read_b128 v[236:239], v147 offset:5120
	ds_read_b128 v[240:243], v147 offset:6144
	ds_read_b128 v[244:247], v147 offset:7168
	global_load_lds_dwordx4 v[142:143], off
	v_lshl_add_u64 v[142:143], s[28:29], 0, v[136:137]
	s_add_i32 m0, s52, 0xe000
	s_nop 0
	global_load_lds_dwordx4 v[142:143], off
	s_waitcnt vmcnt(8)
	s_waitcnt lgkmcnt(0)
	s_barrier
	s_setprio 1
	s_waitcnt lgkmcnt(0)
	v_mfma_f32_16x16x32_bf16 v[124:127], v[138:141], v[216:219], v[124:127]
	v_mfma_f32_16x16x32_bf16 v[120:123], v[152:155], v[216:219], v[120:123]
	v_mfma_f32_16x16x32_bf16 v[108:111], v[138:141], v[224:227], v[108:111]
	v_mfma_f32_16x16x32_bf16 v[104:107], v[152:155], v[224:227], v[104:107]
	v_mfma_f32_16x16x32_bf16 v[92:95], v[138:141], v[232:235], v[92:95]
	v_mfma_f32_16x16x32_bf16 v[88:91], v[152:155], v[232:235], v[88:91]
	v_mfma_f32_16x16x32_bf16 v[76:79], v[138:141], v[240:243], v[76:79]
	v_mfma_f32_16x16x32_bf16 v[72:75], v[152:155], v[240:243], v[72:75]
	v_mfma_f32_16x16x32_bf16 v[124:127], v[148:151], v[220:223], v[124:127]
	v_mfma_f32_16x16x32_bf16 v[120:123], v[156:159], v[220:223], v[120:123]
	v_mfma_f32_16x16x32_bf16 v[108:111], v[148:151], v[228:231], v[108:111]
	v_mfma_f32_16x16x32_bf16 v[104:107], v[156:159], v[228:231], v[104:107]
	v_mfma_f32_16x16x32_bf16 v[92:95], v[148:151], v[236:239], v[92:95]
	v_mfma_f32_16x16x32_bf16 v[88:91], v[156:159], v[236:239], v[88:91]
	v_mfma_f32_16x16x32_bf16 v[76:79], v[148:151], v[244:247], v[76:79]
	v_mfma_f32_16x16x32_bf16 v[72:75], v[156:159], v[244:247], v[72:75]
	s_setprio 0
	s_setprio 1
	v_mfma_f32_16x16x32_bf16 v[116:119], v[200:203], v[216:219], v[116:119]
	v_mfma_f32_16x16x32_bf16 v[112:115], v[208:211], v[216:219], v[112:115]
	v_mfma_f32_16x16x32_bf16 v[100:103], v[200:203], v[224:227], v[100:103]
	v_mfma_f32_16x16x32_bf16 v[96:99], v[208:211], v[224:227], v[96:99]
	v_mfma_f32_16x16x32_bf16 v[84:87], v[200:203], v[232:235], v[84:87]
	v_mfma_f32_16x16x32_bf16 v[80:83], v[208:211], v[232:235], v[80:83]
	v_mfma_f32_16x16x32_bf16 v[68:71], v[200:203], v[240:243], v[68:71]
	v_mfma_f32_16x16x32_bf16 v[64:67], v[208:211], v[240:243], v[64:67]
	v_mfma_f32_16x16x32_bf16 v[116:119], v[204:207], v[220:223], v[116:119]
	v_mfma_f32_16x16x32_bf16 v[112:115], v[212:215], v[220:223], v[112:115]
	v_mfma_f32_16x16x32_bf16 v[100:103], v[204:207], v[228:231], v[100:103]
	v_mfma_f32_16x16x32_bf16 v[96:99], v[212:215], v[228:231], v[96:99]
	v_mfma_f32_16x16x32_bf16 v[84:87], v[204:207], v[236:239], v[84:87]
	v_mfma_f32_16x16x32_bf16 v[80:83], v[212:215], v[236:239], v[80:83]
	v_mfma_f32_16x16x32_bf16 v[68:71], v[204:207], v[244:247], v[68:71]
	v_mfma_f32_16x16x32_bf16 v[64:67], v[212:215], v[244:247], v[64:67]
	s_setprio 0
	s_barrier
	s_add_i32 s68, s68, s49
	v_lshl_add_u64 v[142:143], s[36:37], 0, v[160:161]
	s_mov_b32 m0, s68
	ds_read_b128 v[216:219], v147 offset:16384
	ds_read_b128 v[220:223], v147 offset:17408
	ds_read_b128 v[224:227], v147 offset:18432
	ds_read_b128 v[228:231], v147 offset:19456
	ds_read_b128 v[232:235], v147 offset:20480
	ds_read_b128 v[236:239], v147 offset:21504
	ds_read_b128 v[240:243], v147 offset:22528
	ds_read_b128 v[244:247], v147 offset:23552
	global_load_lds_dwordx4 v[142:143], off
	s_add_i32 m0, s68, 0x2000
	s_add_u32 s68, s36, 0x40000
	v_lshl_add_u64 v[170:171], s[36:37], 0, v[128:129]
	s_addc_u32 s69, s37, 0
	s_add_i32 s70, s70, s49
	global_load_lds_dwordx4 v[170:171], off
	v_lshl_add_u64 v[174:175], s[68:69], 0, v[160:161]
	s_mov_b32 m0, s70
	v_lshl_add_u64 v[198:199], s[38:39], 0, v[130:131]
	global_load_lds_dwordx4 v[174:175], off
	v_lshl_add_u64 v[174:175], s[68:69], 0, v[128:129]
	s_add_i32 m0, s70, 0x2000
	s_nop 0
	global_load_lds_dwordx4 v[174:175], off
	v_lshl_add_u64 v[174:175], s[38:39], 0, v[132:133]
	s_mov_b32 m0, s52
	s_nop 0
	global_load_lds_dwordx4 v[174:175], off
	s_mov_b32 m0, s53
	s_nop 0
	global_load_lds_dwordx4 v[198:199], off
	s_waitcnt vmcnt(8)
	s_waitcnt lgkmcnt(0)
	s_barrier
	s_setprio 1
	s_waitcnt lgkmcnt(0)
	v_mfma_f32_16x16x32_bf16 v[60:63], v[138:141], v[216:219], v[60:63]
	v_mfma_f32_16x16x32_bf16 v[56:59], v[152:155], v[216:219], v[56:59]
	v_mfma_f32_16x16x32_bf16 v[44:47], v[138:141], v[224:227], v[44:47]
	v_mfma_f32_16x16x32_bf16 v[40:43], v[152:155], v[224:227], v[40:43]
	v_mfma_f32_16x16x32_bf16 v[28:31], v[138:141], v[232:235], v[28:31]
	v_mfma_f32_16x16x32_bf16 v[24:27], v[152:155], v[232:235], v[24:27]
	v_mfma_f32_16x16x32_bf16 v[12:15], v[138:141], v[240:243], v[12:15]
	v_mfma_f32_16x16x32_bf16 v[8:11], v[152:155], v[240:243], v[8:11]
	v_mfma_f32_16x16x32_bf16 v[60:63], v[148:151], v[220:223], v[60:63]
	v_mfma_f32_16x16x32_bf16 v[56:59], v[156:159], v[220:223], v[56:59]
	v_mfma_f32_16x16x32_bf16 v[44:47], v[148:151], v[228:231], v[44:47]
	v_mfma_f32_16x16x32_bf16 v[40:43], v[156:159], v[228:231], v[40:43]
	v_mfma_f32_16x16x32_bf16 v[28:31], v[148:151], v[236:239], v[28:31]
	v_mfma_f32_16x16x32_bf16 v[24:27], v[156:159], v[236:239], v[24:27]
	v_mfma_f32_16x16x32_bf16 v[12:15], v[148:151], v[244:247], v[12:15]
	v_mfma_f32_16x16x32_bf16 v[8:11], v[156:159], v[244:247], v[8:11]
	s_setprio 0
	s_setprio 1
	v_mfma_f32_16x16x32_bf16 v[52:55], v[200:203], v[216:219], v[52:55]
	v_mfma_f32_16x16x32_bf16 v[48:51], v[208:211], v[216:219], v[48:51]
	v_mfma_f32_16x16x32_bf16 v[36:39], v[200:203], v[224:227], v[36:39]
	v_mfma_f32_16x16x32_bf16 v[32:35], v[208:211], v[224:227], v[32:35]
	v_mfma_f32_16x16x32_bf16 v[20:23], v[200:203], v[232:235], v[20:23]
	v_mfma_f32_16x16x32_bf16 v[16:19], v[208:211], v[232:235], v[16:19]
	v_mfma_f32_16x16x32_bf16 v[4:7], v[200:203], v[240:243], v[4:7]
	v_mfma_f32_16x16x32_bf16 v[0:3], v[208:211], v[240:243], v[0:3]
	v_mfma_f32_16x16x32_bf16 v[52:55], v[204:207], v[220:223], v[52:55]
	v_mfma_f32_16x16x32_bf16 v[48:51], v[212:215], v[220:223], v[48:51]
	v_mfma_f32_16x16x32_bf16 v[36:39], v[204:207], v[228:231], v[36:39]
	v_mfma_f32_16x16x32_bf16 v[32:35], v[212:215], v[228:231], v[32:35]
	v_mfma_f32_16x16x32_bf16 v[20:23], v[204:207], v[236:239], v[20:23]
	v_mfma_f32_16x16x32_bf16 v[16:19], v[212:215], v[236:239], v[16:19]
	v_mfma_f32_16x16x32_bf16 v[4:7], v[204:207], v[244:247], v[4:7]
	v_mfma_f32_16x16x32_bf16 v[0:3], v[212:215], v[244:247], v[0:3]
	s_setprio 0
	s_barrier
	s_add_i32 s68, s46, 0x120
	s_add_i32 s69, s47, 0x120
	v_add_u32_e32 v156, s68, v145
	v_add_u32_e32 v172, s69, v145
	ds_read_b128 v[138:141], v156
	ds_read_b128 v[148:151], v156 offset:1024
	ds_read_b128 v[152:155], v156 offset:2048
	ds_read_b128 v[156:159], v156 offset:3072
	ds_read_b128 v[200:203], v172
	ds_read_b128 v[204:207], v172 offset:1024
	ds_read_b128 v[208:211], v172 offset:2048
	ds_read_b128 v[212:215], v172 offset:3072
	s_add_u32 s38, s38, 0x40000
	s_addc_u32 s39, s39, 0
	s_mov_b32 m0, s56
	v_lshl_add_u64 v[248:249], s[38:39], 0, v[132:133]
	ds_read_b128 v[216:219], v147 offset:32768
	ds_read_b128 v[220:223], v147 offset:33792
	ds_read_b128 v[224:227], v147 offset:34816
	ds_read_b128 v[228:231], v147 offset:35840
	ds_read_b128 v[232:235], v147 offset:36864
	ds_read_b128 v[236:239], v147 offset:37888
	ds_read_b128 v[240:243], v147 offset:38912
	ds_read_b128 v[244:247], v147 offset:39936
	global_load_lds_dwordx4 v[248:249], off
	v_lshl_add_u64 v[248:249], s[38:39], 0, v[130:131]
	s_mov_b32 m0, s57
	s_nop 0
	global_load_lds_dwordx4 v[248:249], off
	s_waitcnt vmcnt(8)
	s_waitcnt lgkmcnt(0)
	s_barrier
	s_setprio 1
	s_waitcnt lgkmcnt(0)
	v_mfma_f32_16x16x32_bf16 v[124:127], v[138:141], v[216:219], v[124:127]
	v_mfma_f32_16x16x32_bf16 v[120:123], v[152:155], v[216:219], v[120:123]
	v_mfma_f32_16x16x32_bf16 v[108:111], v[138:141], v[224:227], v[108:111]
	v_mfma_f32_16x16x32_bf16 v[104:107], v[152:155], v[224:227], v[104:107]
	v_mfma_f32_16x16x32_bf16 v[92:95], v[138:141], v[232:235], v[92:95]
	v_mfma_f32_16x16x32_bf16 v[88:91], v[152:155], v[232:235], v[88:91]
	v_mfma_f32_16x16x32_bf16 v[76:79], v[138:141], v[240:243], v[76:79]
	v_mfma_f32_16x16x32_bf16 v[72:75], v[152:155], v[240:243], v[72:75]
	v_mfma_f32_16x16x32_bf16 v[124:127], v[148:151], v[220:223], v[124:127]
	v_mfma_f32_16x16x32_bf16 v[120:123], v[156:159], v[220:223], v[120:123]
	v_mfma_f32_16x16x32_bf16 v[108:111], v[148:151], v[228:231], v[108:111]
	v_mfma_f32_16x16x32_bf16 v[104:107], v[156:159], v[228:231], v[104:107]
	v_mfma_f32_16x16x32_bf16 v[92:95], v[148:151], v[236:239], v[92:95]
	v_mfma_f32_16x16x32_bf16 v[88:91], v[156:159], v[236:239], v[88:91]
	v_mfma_f32_16x16x32_bf16 v[76:79], v[148:151], v[244:247], v[76:79]
	v_mfma_f32_16x16x32_bf16 v[72:75], v[156:159], v[244:247], v[72:75]
	s_setprio 0
	s_setprio 1
	v_mfma_f32_16x16x32_bf16 v[116:119], v[200:203], v[216:219], v[116:119]
	v_mfma_f32_16x16x32_bf16 v[112:115], v[208:211], v[216:219], v[112:115]
	v_mfma_f32_16x16x32_bf16 v[100:103], v[200:203], v[224:227], v[100:103]
	v_mfma_f32_16x16x32_bf16 v[96:99], v[208:211], v[224:227], v[96:99]
	v_mfma_f32_16x16x32_bf16 v[84:87], v[200:203], v[232:235], v[84:87]
	v_mfma_f32_16x16x32_bf16 v[80:83], v[208:211], v[232:235], v[80:83]
	v_mfma_f32_16x16x32_bf16 v[68:71], v[200:203], v[240:243], v[68:71]
	v_mfma_f32_16x16x32_bf16 v[64:67], v[208:211], v[240:243], v[64:67]
	v_mfma_f32_16x16x32_bf16 v[116:119], v[204:207], v[220:223], v[116:119]
	v_mfma_f32_16x16x32_bf16 v[112:115], v[212:215], v[220:223], v[112:115]
	v_mfma_f32_16x16x32_bf16 v[100:103], v[204:207], v[228:231], v[100:103]
	v_mfma_f32_16x16x32_bf16 v[96:99], v[212:215], v[228:231], v[96:99]
	v_mfma_f32_16x16x32_bf16 v[84:87], v[204:207], v[236:239], v[84:87]
	v_mfma_f32_16x16x32_bf16 v[80:83], v[212:215], v[236:239], v[80:83]
	v_mfma_f32_16x16x32_bf16 v[68:71], v[204:207], v[244:247], v[68:71]
	v_mfma_f32_16x16x32_bf16 v[64:67], v[212:215], v[244:247], v[64:67]
	s_setprio 0
	s_barrier
	s_add_i32 s38, s68, s49
	v_lshl_add_u64 v[142:143], v[142:143], 0, s[88:89]
	s_mov_b32 m0, s38
	ds_read_b128 v[216:219], v147 offset:49152
	ds_read_b128 v[220:223], v147 offset:50176
	ds_read_b128 v[224:227], v147 offset:51200
	ds_read_b128 v[228:231], v147 offset:52224
	ds_read_b128 v[232:235], v147 offset:53248
	ds_read_b128 v[236:239], v147 offset:54272
	ds_read_b128 v[240:243], v147 offset:55296
	ds_read_b128 v[244:247], v147 offset:56320
	global_load_lds_dwordx4 v[142:143], off
	s_add_i32 m0, s38, 0x2000
	s_add_u32 s36, s36, 0x40080
	v_lshl_add_u64 v[142:143], v[170:171], 0, s[88:89]
	s_addc_u32 s37, s37, 0
	s_add_i32 s38, s69, s49
	global_load_lds_dwordx4 v[142:143], off
	v_lshl_add_u64 v[142:143], s[36:37], 0, v[160:161]
	s_mov_b32 m0, s38
	s_nop 0
	global_load_lds_dwordx4 v[142:143], off
	v_lshl_add_u64 v[142:143], s[36:37], 0, v[128:129]
	s_add_i32 m0, s38, 0x2000
	s_nop 0
	global_load_lds_dwordx4 v[142:143], off
	v_lshl_add_u64 v[142:143], v[174:175], 0, s[88:89]
	s_mov_b32 m0, s58
	s_nop 0
	global_load_lds_dwordx4 v[142:143], off
	v_lshl_add_u64 v[142:143], v[198:199], 0, s[88:89]
	s_mov_b32 m0, s59
	s_nop 0
	global_load_lds_dwordx4 v[142:143], off
	s_waitcnt vmcnt(8)
	s_waitcnt lgkmcnt(0)
	s_barrier
	s_setprio 1
	s_waitcnt lgkmcnt(0)
	v_mfma_f32_16x16x32_bf16 v[60:63], v[138:141], v[216:219], v[60:63]
	v_mfma_f32_16x16x32_bf16 v[56:59], v[152:155], v[216:219], v[56:59]
	v_mfma_f32_16x16x32_bf16 v[44:47], v[138:141], v[224:227], v[44:47]
	v_mfma_f32_16x16x32_bf16 v[40:43], v[152:155], v[224:227], v[40:43]
	v_mfma_f32_16x16x32_bf16 v[28:31], v[138:141], v[232:235], v[28:31]
	v_mfma_f32_16x16x32_bf16 v[24:27], v[152:155], v[232:235], v[24:27]
	v_mfma_f32_16x16x32_bf16 v[12:15], v[138:141], v[240:243], v[12:15]
	v_mfma_f32_16x16x32_bf16 v[8:11], v[152:155], v[240:243], v[8:11]
	v_mfma_f32_16x16x32_bf16 v[60:63], v[148:151], v[220:223], v[60:63]
	v_mfma_f32_16x16x32_bf16 v[56:59], v[156:159], v[220:223], v[56:59]
	v_mfma_f32_16x16x32_bf16 v[44:47], v[148:151], v[228:231], v[44:47]
	v_mfma_f32_16x16x32_bf16 v[40:43], v[156:159], v[228:231], v[40:43]
	v_mfma_f32_16x16x32_bf16 v[28:31], v[148:151], v[236:239], v[28:31]
	v_mfma_f32_16x16x32_bf16 v[24:27], v[156:159], v[236:239], v[24:27]
	v_mfma_f32_16x16x32_bf16 v[12:15], v[148:151], v[244:247], v[12:15]
	v_mfma_f32_16x16x32_bf16 v[8:11], v[156:159], v[244:247], v[8:11]
	s_setprio 0
	s_setprio 1
	v_mfma_f32_16x16x32_bf16 v[52:55], v[200:203], v[216:219], v[52:55]
	v_mfma_f32_16x16x32_bf16 v[48:51], v[208:211], v[216:219], v[48:51]
	v_mfma_f32_16x16x32_bf16 v[36:39], v[200:203], v[224:227], v[36:39]
	v_mfma_f32_16x16x32_bf16 v[32:35], v[208:211], v[224:227], v[32:35]
	v_mfma_f32_16x16x32_bf16 v[20:23], v[200:203], v[232:235], v[20:23]
	v_mfma_f32_16x16x32_bf16 v[16:19], v[208:211], v[232:235], v[16:19]
	v_mfma_f32_16x16x32_bf16 v[4:7], v[200:203], v[240:243], v[4:7]
	v_mfma_f32_16x16x32_bf16 v[0:3], v[208:211], v[240:243], v[0:3]
	v_mfma_f32_16x16x32_bf16 v[52:55], v[204:207], v[220:223], v[52:55]
	v_mfma_f32_16x16x32_bf16 v[48:51], v[212:215], v[220:223], v[48:51]
	v_mfma_f32_16x16x32_bf16 v[36:39], v[204:207], v[228:231], v[36:39]
	v_mfma_f32_16x16x32_bf16 v[32:35], v[212:215], v[228:231], v[32:35]
	v_mfma_f32_16x16x32_bf16 v[20:23], v[204:207], v[236:239], v[20:23]
	v_mfma_f32_16x16x32_bf16 v[16:19], v[212:215], v[236:239], v[16:19]
	v_mfma_f32_16x16x32_bf16 v[4:7], v[204:207], v[244:247], v[4:7]
	v_mfma_f32_16x16x32_bf16 v[0:3], v[212:215], v[244:247], v[0:3]
	s_setprio 0
	s_barrier
	s_add_i32 s67, s67, 2
	s_add_u32 s28, s28, 0x100
	s_addc_u32 s29, s29, 0
	s_add_u32 s63, s63, 0x100
	s_addc_u32 s66, s66, 0
	s_cmp_gt_u32 s67, 13
	s_cbranch_scc0 .LBB0_568
	v_lshl_add_u32 v142, s51, 8, v144
	v_lshl_or_b32 v140, s1, 8, v146
	v_ashrrev_i32_e32 v143, 31, v142
	v_ashrrev_i32_e32 v141, 31, v140
	v_lshlrev_b64 v[138:139], 10, v[142:143]
	v_lshl_add_u64 v[138:139], v[138:139], 0, v[140:141]
	v_lshlrev_b64 v[156:157], 2, v[138:139]
	v_lshl_add_u64 v[158:159], s[16:17], 0, v[156:157]
	v_mov_b32_e32 v248, v158
	v_mov_b32_e32 v249, v159
	global_load_dwordx4 v[200:203], v[248:249], off
	global_load_dwordx4 v[204:207], v[248:249], off offset:16
	global_load_dwordx4 v[208:211], v[248:249], off offset:512
	global_load_dwordx4 v[212:215], v[248:249], off offset:528
	s_mov_b64 s[98:99], 0x10000
	v_lshl_add_u64 v[250:251], v[248:249], 0, s[98:99]
	global_load_dwordx4 v[216:219], v[250:251], off
	global_load_dwordx4 v[220:223], v[250:251], off offset:16
	global_load_dwordx4 v[224:227], v[250:251], off offset:512
	global_load_dwordx4 v[228:231], v[250:251], off offset:528
	s_mov_b64 s[98:99], 0x20000
	v_lshl_add_u64 v[250:251], v[248:249], 0, s[98:99]
	global_load_dwordx4 v[232:235], v[250:251], off
	global_load_dwordx4 v[236:239], v[250:251], off offset:16
	global_load_dwordx4 v[240:243], v[250:251], off offset:512
	global_load_dwordx4 v[244:247], v[250:251], off offset:528
	s_waitcnt vmcnt(8)
	s_nop 1
	s_nop 1
	v_pk_add_f32 v[122:123], v[122:123], v[206:207]
	v_pk_add_f32 v[126:127], v[126:127], v[202:203]
	v_pk_add_f32 v[124:125], v[124:125], v[200:201]
	v_lshl_add_u64 v[152:153], s[12:13], 0, v[156:157]
	v_pk_add_f32 v[120:121], v[120:121], v[204:205]
	global_store_dwordx4 v[152:153], v[124:127], off
	global_store_dwordx4 v[152:153], v[120:123], off offset:16
	v_cvt_pk_bf16_f32 v148, v124, v125
	v_mul_f32_e32 v125, v125, v125
	v_fmac_f32_e32 v125, v124, v124
	v_mul_f32_e32 v124, v127, v127
	v_cvt_pk_bf16_f32 v150, v120, v121
	v_fmac_f32_e32 v124, v126, v126
	v_mul_f32_e32 v121, v121, v121
	v_add_f32_e32 v124, v125, v124
	v_fmac_f32_e32 v121, v120, v120
	v_cvt_pk_bf16_f32 v149, v126, v127
	v_cvt_pk_bf16_f32 v151, v122, v123
	v_lshl_add_u64 v[154:155], v[138:139], 1, s[18:19]
	v_add_f32_e32 v120, v124, v121
	v_mul_f32_e32 v121, v123, v123
	global_store_dwordx4 v[154:155], v[148:151], off
	v_fmac_f32_e32 v121, v122, v122
	s_nop 0
	v_add_f32_e32 v148, v121, v120
	s_nop 1
	s_nop 1
	v_pk_add_f32 v[114:115], v[114:115], v[214:215]
	v_pk_add_f32 v[118:119], v[118:119], v[210:211]
	v_pk_add_f32 v[116:117], v[116:117], v[208:209]
	v_pk_add_f32 v[112:113], v[112:113], v[212:213]
	global_store_dwordx4 v[152:153], v[116:119], off offset:512
	global_store_dwordx4 v[152:153], v[112:115], off offset:528
	v_cvt_pk_bf16_f32 v123, v114, v115
	v_cvt_pk_bf16_f32 v120, v116, v117
	v_mul_f32_e32 v115, v115, v115
	v_fmac_f32_e32 v115, v114, v114
	v_mul_f32_e32 v114, v117, v117
	v_fmac_f32_e32 v114, v116, v116
	v_mul_f32_e32 v116, v119, v119
	v_cvt_pk_bf16_f32 v122, v112, v113
	v_fmac_f32_e32 v116, v118, v118
	v_mul_f32_e32 v113, v113, v113
	v_add_f32_e32 v114, v114, v116
	v_fmac_f32_e32 v113, v112, v112
	v_add_f32_e32 v112, v114, v113
	v_add_f32_e32 v112, v115, v112
	v_add_f32_e32 v112, v148, v112
	ds_bpermute_b32 v113, v180, v112
	v_cvt_pk_bf16_f32 v121, v118, v119
	global_store_dwordx4 v[154:155], v[120:123], off offset:256
	s_waitcnt lgkmcnt(0)
	v_add_f32_e32 v114, v112, v113
	ds_bpermute_b32 v115, v181, v114
	v_lshl_add_u64 v[112:113], v[142:143], 3, s[14:15]
	s_and_saveexec_b64 s[28:29], s[8:9]
	s_cbranch_execz .LBB0_571
	s_waitcnt lgkmcnt(0)
	v_add_f32_e32 v114, v114, v115
	v_fma_f32 v114, v114, s65, 0.5
	v_trunc_f32_e32 v114, v114
	v_mul_f32_e32 v115, 0x2f800000, v114
	v_floor_f32_e32 v115, v115
	v_fmac_f32_e32 v114, 0xcf800000, v115
	v_cvt_u32_f32_e32 v114, v114
	v_cvt_u32_f32_e32 v115, v115
	global_atomic_add_x2 v[112:113], v[114:115], off
.LBB0_571:
	s_or_b64 exec, exec, s[28:29]
	v_or_b32_e32 v114, 16, v142
	s_waitcnt lgkmcnt(0)
	v_ashrrev_i32_e32 v115, 31, v114
	v_lshlrev_b64 v[114:115], 10, v[114:115]
	v_lshl_add_u64 v[122:123], v[114:115], 0, v[140:141]
	v_lshlrev_b64 v[124:125], 2, v[122:123]
	v_lshl_add_u64 v[126:127], s[16:17], 0, v[124:125]
	s_mov_b64 s[98:99], 0x30000
	v_lshl_add_u64 v[250:251], v[248:249], 0, s[98:99]
	global_load_dwordx4 v[200:203], v[250:251], off
	global_load_dwordx4 v[204:207], v[250:251], off offset:16
	global_load_dwordx4 v[208:211], v[250:251], off offset:512
	global_load_dwordx4 v[212:215], v[250:251], off offset:528
	s_waitcnt vmcnt(12)
	s_nop 1
	s_nop 1
	v_lshl_add_u64 v[122:123], v[122:123], 1, s[18:19]
	v_lshl_add_u64 v[124:125], s[12:13], 0, v[124:125]
	v_pk_add_f32 v[110:111], v[110:111], v[218:219]
	v_pk_add_f32 v[108:109], v[108:109], v[216:217]
	v_pk_add_f32 v[106:107], v[106:107], v[222:223]
	v_pk_add_f32 v[104:105], v[104:105], v[220:221]
	v_cvt_pk_bf16_f32 v114, v108, v109
	v_cvt_pk_bf16_f32 v115, v110, v111
	v_cvt_pk_bf16_f32 v116, v104, v105
	v_cvt_pk_bf16_f32 v117, v106, v107
	global_store_dwordx4 v[124:125], v[108:111], off
	global_store_dwordx4 v[124:125], v[104:107], off offset:16
	global_store_dwordx4 v[122:123], v[114:117], off
	s_nop 1
	s_nop 0
	s_nop 1
	v_mul_f32_e32 v109, v109, v109
	v_mul_f32_e32 v111, v111, v111
	v_mul_f32_e32 v105, v105, v105
	v_fmac_f32_e32 v109, v108, v108
	v_fmac_f32_e32 v111, v110, v110
	v_mul_f32_e32 v107, v107, v107
	v_fmac_f32_e32 v105, v104, v104
	v_add_f32_e32 v104, v109, v111
	v_fmac_f32_e32 v107, v106, v106
	v_add_f32_e32 v104, v104, v105
	v_add_f32_e32 v108, v107, v104
	v_pk_add_f32 v[102:103], v[102:103], v[226:227]
	v_pk_add_f32 v[100:101], v[100:101], v[224:225]
	v_pk_add_f32 v[106:107], v[98:99], v[230:231]
	v_pk_add_f32 v[104:105], v[96:97], v[228:229]
	v_mul_f32_e32 v97, v101, v101
	v_mul_f32_e32 v98, v103, v103
	v_mul_f32_e32 v99, v105, v105
	v_fmac_f32_e32 v97, v100, v100
	v_fmac_f32_e32 v98, v102, v102
	v_mul_f32_e32 v96, v107, v107
	v_add_f32_e32 v97, v97, v98
	v_fmac_f32_e32 v99, v104, v104
	v_fmac_f32_e32 v96, v106, v106
	v_add_f32_e32 v97, v97, v99
	v_add_f32_e32 v96, v96, v97
	v_add_f32_e32 v96, v108, v96
	ds_bpermute_b32 v97, v180, v96
	global_store_dwordx4 v[124:125], v[100:103], off offset:512
	global_store_dwordx4 v[124:125], v[104:107], off offset:528
	v_cvt_pk_bf16_f32 v98, v100, v101
	v_cvt_pk_bf16_f32 v99, v102, v103
	v_cvt_pk_bf16_f32 v100, v104, v105
	s_waitcnt lgkmcnt(0)
	v_add_f32_e32 v96, v96, v97
	ds_bpermute_b32 v97, v181, v96
	v_cvt_pk_bf16_f32 v101, v106, v107
	global_store_dwordx4 v[122:123], v[98:101], off offset:256
	s_and_saveexec_b64 s[28:29], s[8:9]
	v_readlane_b32 s62, v254, 61
	v_readlane_b32 s66, v254, 63
	v_readlane_b32 s38, v254, 59
	v_readlane_b32 s63, v254, 62
	v_readlane_b32 s67, v255, 0
	v_readlane_b32 s39, v254, 60
	s_cbranch_execz .LBB0_573
	s_waitcnt lgkmcnt(0)
	v_add_f32_e32 v96, v96, v97
	v_fma_f32 v96, v96, s65, 0.5
	v_trunc_f32_e32 v96, v96
	v_mul_f32_e32 v97, 0x2f800000, v96
	v_floor_f32_e32 v97, v97
	v_fmac_f32_e32 v96, 0xcf800000, v97
	v_cvt_u32_f32_e32 v96, v96
	v_cvt_u32_f32_e32 v97, v97
	global_atomic_add_x2 v[112:113], v[96:97], off offset:128
.LBB0_573:
	s_or_b64 exec, exec, s[28:29]
	v_or_b32_e32 v96, 32, v142
	s_waitcnt lgkmcnt(0)
	v_ashrrev_i32_e32 v97, 31, v96
	v_lshlrev_b64 v[96:97], 10, v[96:97]
	v_lshl_add_u64 v[104:105], v[96:97], 0, v[140:141]
	v_lshlrev_b64 v[106:107], 2, v[104:105]
	v_lshl_add_u64 v[108:109], s[16:17], 0, v[106:107]
	s_mov_b64 s[98:99], 0x80000
	v_lshl_add_u64 v[250:251], v[248:249], 0, s[98:99]
	global_load_dwordx4 v[216:219], v[250:251], off
	global_load_dwordx4 v[220:223], v[250:251], off offset:16
	global_load_dwordx4 v[224:227], v[250:251], off offset:512
	global_load_dwordx4 v[228:231], v[250:251], off offset:528
	s_waitcnt vmcnt(16)
	s_nop 1
	s_nop 1
	v_lshl_add_u64 v[104:105], v[104:105], 1, s[18:19]
	v_lshl_add_u64 v[106:107], s[12:13], 0, v[106:107]
	v_pk_add_f32 v[94:95], v[94:95], v[234:235]
	v_pk_add_f32 v[92:93], v[92:93], v[232:233]
	v_pk_add_f32 v[90:91], v[90:91], v[238:239]
	v_pk_add_f32 v[88:89], v[88:89], v[236:237]
	v_cvt_pk_bf16_f32 v96, v92, v93
	v_cvt_pk_bf16_f32 v97, v94, v95
	v_cvt_pk_bf16_f32 v98, v88, v89
	v_cvt_pk_bf16_f32 v99, v90, v91
	global_store_dwordx4 v[106:107], v[92:95], off
	global_store_dwordx4 v[106:107], v[88:91], off offset:16
	global_store_dwordx4 v[104:105], v[96:99], off
	s_nop 1
	s_nop 0
	s_nop 1
	v_mul_f32_e32 v93, v93, v93
	v_mul_f32_e32 v95, v95, v95
	v_mul_f32_e32 v89, v89, v89
	v_fmac_f32_e32 v93, v92, v92
	v_fmac_f32_e32 v95, v94, v94
	v_mul_f32_e32 v91, v91, v91
	v_fmac_f32_e32 v89, v88, v88
	v_add_f32_e32 v88, v93, v95
	v_fmac_f32_e32 v91, v90, v90
	v_add_f32_e32 v88, v88, v89
	v_add_f32_e32 v92, v91, v88
	v_pk_add_f32 v[86:87], v[86:87], v[242:243]
	v_pk_add_f32 v[84:85], v[84:85], v[240:241]
	v_pk_add_f32 v[90:91], v[82:83], v[246:247]
	v_pk_add_f32 v[88:89], v[80:81], v[244:245]
	v_mul_f32_e32 v81, v85, v85
	v_mul_f32_e32 v82, v87, v87
	v_mul_f32_e32 v83, v89, v89
	v_fmac_f32_e32 v81, v84, v84
	v_fmac_f32_e32 v82, v86, v86
	v_mul_f32_e32 v80, v91, v91
	v_add_f32_e32 v81, v81, v82
	v_fmac_f32_e32 v83, v88, v88
	v_fmac_f32_e32 v80, v90, v90
	v_add_f32_e32 v81, v81, v83
	v_add_f32_e32 v80, v80, v81
	v_add_f32_e32 v80, v92, v80
	ds_bpermute_b32 v81, v180, v80
	global_store_dwordx4 v[106:107], v[84:87], off offset:512
	global_store_dwordx4 v[106:107], v[88:91], off offset:528
	v_cvt_pk_bf16_f32 v82, v84, v85
	v_cvt_pk_bf16_f32 v83, v86, v87
	v_cvt_pk_bf16_f32 v84, v88, v89
	s_waitcnt lgkmcnt(0)
	v_add_f32_e32 v80, v80, v81
	ds_bpermute_b32 v81, v181, v80
	v_cvt_pk_bf16_f32 v85, v90, v91
	global_store_dwordx4 v[104:105], v[82:85], off offset:256
	s_and_saveexec_b64 s[28:29], s[8:9]
	s_cbranch_execz .LBB0_575
	s_waitcnt lgkmcnt(0)
	v_add_f32_e32 v80, v80, v81
	v_fma_f32 v80, v80, s65, 0.5
	v_trunc_f32_e32 v80, v80
	v_mul_f32_e32 v81, 0x2f800000, v80
	v_floor_f32_e32 v81, v81
	v_fmac_f32_e32 v80, 0xcf800000, v81
	v_cvt_u32_f32_e32 v80, v80
	v_cvt_u32_f32_e32 v81, v81
	global_atomic_add_x2 v[112:113], v[80:81], off offset:256
.LBB0_575:
	s_or_b64 exec, exec, s[28:29]
	v_or_b32_e32 v80, 48, v142
	s_waitcnt lgkmcnt(0)
	v_ashrrev_i32_e32 v81, 31, v80
	v_lshlrev_b64 v[80:81], 10, v[80:81]
	v_lshl_add_u64 v[88:89], v[80:81], 0, v[140:141]
	v_lshlrev_b64 v[90:91], 2, v[88:89]
	v_lshl_add_u64 v[92:93], s[16:17], 0, v[90:91]
	s_mov_b64 s[98:99], 0x90000
	v_lshl_add_u64 v[250:251], v[248:249], 0, s[98:99]
	global_load_dwordx4 v[232:235], v[250:251], off
	global_load_dwordx4 v[236:239], v[250:251], off offset:16
	global_load_dwordx4 v[240:243], v[250:251], off offset:512
	global_load_dwordx4 v[244:247], v[250:251], off offset:528
	s_waitcnt vmcnt(16)
	s_nop 1
	s_nop 1
	v_lshl_add_u64 v[88:89], v[88:89], 1, s[18:19]
	v_lshl_add_u64 v[90:91], s[12:13], 0, v[90:91]
	v_pk_add_f32 v[78:79], v[78:79], v[202:203]
	v_pk_add_f32 v[76:77], v[76:77], v[200:201]
	v_pk_add_f32 v[74:75], v[74:75], v[206:207]
	v_pk_add_f32 v[72:73], v[72:73], v[204:205]
	v_cvt_pk_bf16_f32 v80, v76, v77
	v_cvt_pk_bf16_f32 v81, v78, v79
	v_cvt_pk_bf16_f32 v82, v72, v73
	v_cvt_pk_bf16_f32 v83, v74, v75
	global_store_dwordx4 v[90:91], v[76:79], off
	global_store_dwordx4 v[90:91], v[72:75], off offset:16
	global_store_dwordx4 v[88:89], v[80:83], off
	s_nop 1
	s_nop 0
	s_nop 1
	v_mul_f32_e32 v77, v77, v77
	v_mul_f32_e32 v79, v79, v79
	v_mul_f32_e32 v73, v73, v73
	v_fmac_f32_e32 v77, v76, v76
	v_fmac_f32_e32 v79, v78, v78
	v_mul_f32_e32 v75, v75, v75
	v_fmac_f32_e32 v73, v72, v72
	v_add_f32_e32 v72, v77, v79
	v_fmac_f32_e32 v75, v74, v74
	v_add_f32_e32 v72, v72, v73
	v_add_f32_e32 v76, v75, v72
	v_pk_add_f32 v[70:71], v[70:71], v[210:211]
	v_pk_add_f32 v[68:69], v[68:69], v[208:209]
	v_pk_add_f32 v[74:75], v[66:67], v[214:215]
	v_pk_add_f32 v[72:73], v[64:65], v[212:213]
	v_mul_f32_e32 v65, v69, v69
	v_mul_f32_e32 v66, v71, v71
	v_mul_f32_e32 v67, v73, v73
	v_fmac_f32_e32 v65, v68, v68
	v_fmac_f32_e32 v66, v70, v70
	v_mul_f32_e32 v64, v75, v75
	v_add_f32_e32 v65, v65, v66
	v_fmac_f32_e32 v67, v72, v72
	v_fmac_f32_e32 v64, v74, v74
	v_add_f32_e32 v65, v65, v67
	v_add_f32_e32 v64, v64, v65
	v_add_f32_e32 v64, v76, v64
	ds_bpermute_b32 v65, v180, v64
	global_store_dwordx4 v[90:91], v[68:71], off offset:512
	global_store_dwordx4 v[90:91], v[72:75], off offset:528
	v_cvt_pk_bf16_f32 v66, v68, v69
	v_cvt_pk_bf16_f32 v67, v70, v71
	v_cvt_pk_bf16_f32 v68, v72, v73
	s_waitcnt lgkmcnt(0)
	v_add_f32_e32 v64, v64, v65
	ds_bpermute_b32 v65, v181, v64
	v_cvt_pk_bf16_f32 v69, v74, v75
	global_store_dwordx4 v[88:89], v[66:69], off offset:256
	s_and_saveexec_b64 s[28:29], s[8:9]
	s_cbranch_execz .LBB0_577
	s_waitcnt lgkmcnt(0)
	v_add_f32_e32 v64, v64, v65
	v_fma_f32 v64, v64, s65, 0.5
	v_trunc_f32_e32 v64, v64
	v_mul_f32_e32 v65, 0x2f800000, v64
	v_floor_f32_e32 v65, v65
	v_fmac_f32_e32 v64, 0xcf800000, v65
	v_cvt_u32_f32_e32 v64, v64
	v_cvt_u32_f32_e32 v65, v65
	global_atomic_add_x2 v[112:113], v[64:65], off offset:384
.LBB0_577:
	s_or_b64 exec, exec, s[28:29]
	s_mov_b64 s[28:29], 0x20000
	v_lshl_add_u64 v[72:73], v[138:139], 0, s[28:29]
	v_lshlrev_b64 v[74:75], 2, v[72:73]
	v_lshl_add_u64 v[76:77], s[16:17], 0, v[74:75]
	s_waitcnt lgkmcnt(0)
	s_mov_b64 s[98:99], 0xa0000
	v_lshl_add_u64 v[250:251], v[248:249], 0, s[98:99]
	global_load_dwordx4 v[200:203], v[250:251], off
	global_load_dwordx4 v[204:207], v[250:251], off offset:16
	global_load_dwordx4 v[208:211], v[250:251], off offset:512
	global_load_dwordx4 v[212:215], v[250:251], off offset:528
	s_waitcnt vmcnt(16)
	s_nop 1
	s_nop 1
	v_lshl_add_u64 v[72:73], v[72:73], 1, s[18:19]
	v_lshl_add_u64 v[74:75], s[12:13], 0, v[74:75]
	v_pk_add_f32 v[62:63], v[62:63], v[218:219]
	v_pk_add_f32 v[60:61], v[60:61], v[216:217]
	v_pk_add_f32 v[58:59], v[58:59], v[222:223]
	v_pk_add_f32 v[56:57], v[56:57], v[220:221]
	v_cvt_pk_bf16_f32 v64, v60, v61
	v_cvt_pk_bf16_f32 v65, v62, v63
	v_cvt_pk_bf16_f32 v66, v56, v57
	v_cvt_pk_bf16_f32 v67, v58, v59
	global_store_dwordx4 v[74:75], v[60:63], off
	global_store_dwordx4 v[74:75], v[56:59], off offset:16
	global_store_dwordx4 v[72:73], v[64:67], off
	s_nop 1
	s_nop 0
	s_nop 1
	v_mul_f32_e32 v61, v61, v61
	v_mul_f32_e32 v63, v63, v63
	v_mul_f32_e32 v57, v57, v57
	v_fmac_f32_e32 v61, v60, v60
	v_fmac_f32_e32 v63, v62, v62
	v_mul_f32_e32 v59, v59, v59
	v_fmac_f32_e32 v57, v56, v56
	v_add_f32_e32 v56, v61, v63
	v_fmac_f32_e32 v59, v58, v58
	v_add_f32_e32 v56, v56, v57
	v_add_f32_e32 v60, v59, v56
	v_pk_add_f32 v[54:55], v[54:55], v[226:227]
	v_pk_add_f32 v[52:53], v[52:53], v[224:225]
	v_pk_add_f32 v[58:59], v[50:51], v[230:231]
	v_pk_add_f32 v[56:57], v[48:49], v[228:229]
	v_mul_f32_e32 v49, v53, v53
	v_mul_f32_e32 v50, v55, v55
	v_mul_f32_e32 v51, v57, v57
	v_fmac_f32_e32 v49, v52, v52
	v_fmac_f32_e32 v50, v54, v54
	v_mul_f32_e32 v48, v59, v59
	v_add_f32_e32 v49, v49, v50
	v_fmac_f32_e32 v51, v56, v56
	v_fmac_f32_e32 v48, v58, v58
	v_add_f32_e32 v49, v49, v51
	v_add_f32_e32 v48, v48, v49
	v_add_f32_e32 v48, v60, v48
	ds_bpermute_b32 v49, v180, v48
	global_store_dwordx4 v[74:75], v[52:55], off offset:512
	global_store_dwordx4 v[74:75], v[56:59], off offset:528
	v_cvt_pk_bf16_f32 v50, v52, v53
	v_cvt_pk_bf16_f32 v51, v54, v55
	v_cvt_pk_bf16_f32 v52, v56, v57
	s_waitcnt lgkmcnt(0)
	v_add_f32_e32 v48, v48, v49
	ds_bpermute_b32 v49, v181, v48
	v_cvt_pk_bf16_f32 v53, v58, v59
	global_store_dwordx4 v[72:73], v[50:53], off offset:256
	s_and_saveexec_b64 s[28:29], s[8:9]
	s_cbranch_execz .LBB0_579
	s_waitcnt lgkmcnt(0)
	v_add_f32_e32 v48, v48, v49
	v_fma_f32 v48, v48, s65, 0.5
	v_trunc_f32_e32 v48, v48
	v_mul_f32_e32 v49, 0x2f800000, v48
	v_floor_f32_e32 v49, v49
	v_fmac_f32_e32 v48, 0xcf800000, v49
	v_cvt_u32_f32_e32 v48, v48
	v_cvt_u32_f32_e32 v49, v49
	global_atomic_add_x2 v[112:113], v[48:49], off offset:1024
.LBB0_579:
	s_or_b64 exec, exec, s[28:29]
	s_mov_b64 s[28:29], 0x24000
	v_lshl_add_u64 v[56:57], v[138:139], 0, s[28:29]
	v_lshlrev_b64 v[58:59], 2, v[56:57]
	v_lshl_add_u64 v[60:61], s[16:17], 0, v[58:59]
	s_waitcnt lgkmcnt(0)
	s_mov_b64 s[98:99], 0xb0000
	v_lshl_add_u64 v[250:251], v[248:249], 0, s[98:99]
	global_load_dwordx4 v[216:219], v[250:251], off
	global_load_dwordx4 v[220:223], v[250:251], off offset:16
	global_load_dwordx4 v[224:227], v[250:251], off offset:512
	global_load_dwordx4 v[228:231], v[250:251], off offset:528
	s_waitcnt vmcnt(16)
	s_nop 1
	s_nop 1
	v_lshl_add_u64 v[56:57], v[56:57], 1, s[18:19]
	v_lshl_add_u64 v[58:59], s[12:13], 0, v[58:59]
	v_pk_add_f32 v[46:47], v[46:47], v[234:235]
	v_pk_add_f32 v[44:45], v[44:45], v[232:233]
	v_pk_add_f32 v[42:43], v[42:43], v[238:239]
	v_pk_add_f32 v[40:41], v[40:41], v[236:237]
	v_cvt_pk_bf16_f32 v48, v44, v45
	v_cvt_pk_bf16_f32 v49, v46, v47
	v_cvt_pk_bf16_f32 v50, v40, v41
	v_cvt_pk_bf16_f32 v51, v42, v43
	global_store_dwordx4 v[58:59], v[44:47], off
	global_store_dwordx4 v[58:59], v[40:43], off offset:16
	global_store_dwordx4 v[56:57], v[48:51], off
	s_nop 1
	s_nop 0
	s_nop 1
	v_mul_f32_e32 v45, v45, v45
	v_mul_f32_e32 v47, v47, v47
	v_mul_f32_e32 v41, v41, v41
	v_fmac_f32_e32 v45, v44, v44
	v_fmac_f32_e32 v47, v46, v46
	v_mul_f32_e32 v43, v43, v43
	v_fmac_f32_e32 v41, v40, v40
	v_add_f32_e32 v40, v45, v47
	v_fmac_f32_e32 v43, v42, v42
	v_add_f32_e32 v40, v40, v41
	v_add_f32_e32 v44, v43, v40
	v_pk_add_f32 v[38:39], v[38:39], v[242:243]
	v_pk_add_f32 v[36:37], v[36:37], v[240:241]
	v_pk_add_f32 v[42:43], v[34:35], v[246:247]
	v_pk_add_f32 v[40:41], v[32:33], v[244:245]
	v_mul_f32_e32 v33, v37, v37
	v_mul_f32_e32 v34, v39, v39
	v_mul_f32_e32 v35, v41, v41
	v_fmac_f32_e32 v33, v36, v36
	v_fmac_f32_e32 v34, v38, v38
	v_mul_f32_e32 v32, v43, v43
	v_add_f32_e32 v33, v33, v34
	v_fmac_f32_e32 v35, v40, v40
	v_fmac_f32_e32 v32, v42, v42
	v_add_f32_e32 v33, v33, v35
	v_add_f32_e32 v32, v32, v33
	v_add_f32_e32 v32, v44, v32
	ds_bpermute_b32 v33, v180, v32
	global_store_dwordx4 v[58:59], v[36:39], off offset:512
	global_store_dwordx4 v[58:59], v[40:43], off offset:528
	v_cvt_pk_bf16_f32 v34, v36, v37
	v_cvt_pk_bf16_f32 v35, v38, v39
	v_cvt_pk_bf16_f32 v36, v40, v41
	s_waitcnt lgkmcnt(0)
	v_add_f32_e32 v32, v32, v33
	ds_bpermute_b32 v33, v181, v32
	v_cvt_pk_bf16_f32 v37, v42, v43
	global_store_dwordx4 v[56:57], v[34:37], off offset:256
	s_and_saveexec_b64 s[28:29], s[8:9]
	s_cbranch_execz .LBB0_581
	s_waitcnt lgkmcnt(0)
	v_add_f32_e32 v32, v32, v33
	v_fma_f32 v32, v32, s65, 0.5
	v_trunc_f32_e32 v32, v32
	v_mul_f32_e32 v33, 0x2f800000, v32
	v_floor_f32_e32 v33, v33
	v_fmac_f32_e32 v32, 0xcf800000, v33
	v_cvt_u32_f32_e32 v32, v32
	v_cvt_u32_f32_e32 v33, v33
	global_atomic_add_x2 v[112:113], v[32:33], off offset:1152
.LBB0_581:
	s_or_b64 exec, exec, s[28:29]
	s_mov_b64 s[28:29], 0x28000
	v_lshl_add_u64 v[40:41], v[138:139], 0, s[28:29]
	v_lshlrev_b64 v[42:43], 2, v[40:41]
	v_lshl_add_u64 v[44:45], s[16:17], 0, v[42:43]
	s_waitcnt lgkmcnt(0)
	s_waitcnt vmcnt(12)
	s_nop 1
	s_nop 1
	v_lshl_add_u64 v[40:41], v[40:41], 1, s[18:19]
	v_lshl_add_u64 v[42:43], s[12:13], 0, v[42:43]
	v_pk_add_f32 v[30:31], v[30:31], v[202:203]
	v_pk_add_f32 v[28:29], v[28:29], v[200:201]
	v_pk_add_f32 v[26:27], v[26:27], v[206:207]
	v_pk_add_f32 v[24:25], v[24:25], v[204:205]
	v_cvt_pk_bf16_f32 v32, v28, v29
	v_cvt_pk_bf16_f32 v33, v30, v31
	v_cvt_pk_bf16_f32 v34, v24, v25
	v_cvt_pk_bf16_f32 v35, v26, v27
	global_store_dwordx4 v[42:43], v[28:31], off
	global_store_dwordx4 v[42:43], v[24:27], off offset:16
	global_store_dwordx4 v[40:41], v[32:35], off
	s_nop 1
	s_nop 0
	s_nop 1
	v_mul_f32_e32 v29, v29, v29
	v_mul_f32_e32 v31, v31, v31
	v_mul_f32_e32 v25, v25, v25
	v_fmac_f32_e32 v29, v28, v28
	v_fmac_f32_e32 v31, v30, v30
	v_mul_f32_e32 v27, v27, v27
	v_fmac_f32_e32 v25, v24, v24
	v_add_f32_e32 v24, v29, v31
	v_fmac_f32_e32 v27, v26, v26
	v_add_f32_e32 v24, v24, v25
	v_add_f32_e32 v28, v27, v24
	v_pk_add_f32 v[22:23], v[22:23], v[210:211]
	v_pk_add_f32 v[20:21], v[20:21], v[208:209]
	v_pk_add_f32 v[26:27], v[18:19], v[214:215]
	v_pk_add_f32 v[24:25], v[16:17], v[212:213]
	v_mul_f32_e32 v17, v21, v21
	v_mul_f32_e32 v18, v23, v23
	v_mul_f32_e32 v19, v25, v25
	v_fmac_f32_e32 v17, v20, v20
	v_fmac_f32_e32 v18, v22, v22
	v_mul_f32_e32 v16, v27, v27
	v_add_f32_e32 v17, v17, v18
	v_fmac_f32_e32 v19, v24, v24
	v_fmac_f32_e32 v16, v26, v26
	v_add_f32_e32 v17, v17, v19
	v_add_f32_e32 v16, v16, v17
	v_add_f32_e32 v16, v28, v16
	ds_bpermute_b32 v17, v180, v16
	global_store_dwordx4 v[42:43], v[20:23], off offset:512
	global_store_dwordx4 v[42:43], v[24:27], off offset:528
	v_cvt_pk_bf16_f32 v18, v20, v21
	v_cvt_pk_bf16_f32 v19, v22, v23
	v_cvt_pk_bf16_f32 v20, v24, v25
	s_waitcnt lgkmcnt(0)
	v_add_f32_e32 v16, v16, v17
	ds_bpermute_b32 v17, v181, v16
	v_cvt_pk_bf16_f32 v21, v26, v27
	global_store_dwordx4 v[40:41], v[18:21], off offset:256
	s_and_saveexec_b64 s[28:29], s[8:9]
	s_cbranch_execz .LBB0_583
	s_waitcnt lgkmcnt(0)
	v_add_f32_e32 v16, v16, v17
	v_fma_f32 v16, v16, s65, 0.5
	v_trunc_f32_e32 v16, v16
	v_mul_f32_e32 v17, 0x2f800000, v16
	v_floor_f32_e32 v17, v17
	v_fmac_f32_e32 v16, 0xcf800000, v17
	v_cvt_u32_f32_e32 v16, v16
	v_cvt_u32_f32_e32 v17, v17
	global_atomic_add_x2 v[112:113], v[16:17], off offset:1280
.LBB0_583:
	s_or_b64 exec, exec, s[28:29]
	s_mov_b64 s[28:29], 0x2c000
	v_lshl_add_u64 v[24:25], v[138:139], 0, s[28:29]
	v_lshlrev_b64 v[26:27], 2, v[24:25]
	v_lshl_add_u64 v[28:29], s[16:17], 0, v[26:27]
	s_waitcnt lgkmcnt(0)
	s_waitcnt vmcnt(8)
	s_nop 1
	s_nop 1
	v_lshl_add_u64 v[24:25], v[24:25], 1, s[18:19]
	v_lshl_add_u64 v[26:27], s[12:13], 0, v[26:27]
	v_pk_add_f32 v[14:15], v[14:15], v[218:219]
	v_pk_add_f32 v[12:13], v[12:13], v[216:217]
	v_pk_add_f32 v[10:11], v[10:11], v[222:223]
	v_pk_add_f32 v[8:9], v[8:9], v[220:221]
	v_cvt_pk_bf16_f32 v16, v12, v13
	v_cvt_pk_bf16_f32 v17, v14, v15
	v_cvt_pk_bf16_f32 v18, v8, v9
	v_cvt_pk_bf16_f32 v19, v10, v11
	global_store_dwordx4 v[26:27], v[12:15], off
	global_store_dwordx4 v[26:27], v[8:11], off offset:16
	global_store_dwordx4 v[24:25], v[16:19], off
	s_nop 1
	s_nop 0
	s_nop 1
	v_mul_f32_e32 v13, v13, v13
	v_mul_f32_e32 v15, v15, v15
	v_mul_f32_e32 v9, v9, v9
	v_fmac_f32_e32 v13, v12, v12
	v_fmac_f32_e32 v15, v14, v14
	v_mul_f32_e32 v11, v11, v11
	v_fmac_f32_e32 v9, v8, v8
	v_add_f32_e32 v8, v13, v15
	v_fmac_f32_e32 v11, v10, v10
	v_add_f32_e32 v8, v8, v9
	v_add_f32_e32 v12, v11, v8
	v_pk_add_f32 v[6:7], v[6:7], v[226:227]
	v_pk_add_f32 v[4:5], v[4:5], v[224:225]
	v_pk_add_f32 v[10:11], v[2:3], v[230:231]
	v_pk_add_f32 v[8:9], v[0:1], v[228:229]
	v_mul_f32_e32 v1, v5, v5
	v_mul_f32_e32 v2, v7, v7
	v_mul_f32_e32 v3, v9, v9
	v_fmac_f32_e32 v1, v4, v4
	v_fmac_f32_e32 v2, v6, v6
	v_mul_f32_e32 v0, v11, v11
	v_add_f32_e32 v1, v1, v2
	v_fmac_f32_e32 v3, v8, v8
	v_fmac_f32_e32 v0, v10, v10
	v_add_f32_e32 v1, v1, v3
	v_add_f32_e32 v0, v0, v1
	v_add_f32_e32 v0, v12, v0
	ds_bpermute_b32 v1, v180, v0
	global_store_dwordx4 v[26:27], v[4:7], off offset:512
	global_store_dwordx4 v[26:27], v[8:11], off offset:528
	v_cvt_pk_bf16_f32 v2, v4, v5
	v_cvt_pk_bf16_f32 v3, v6, v7
	v_cvt_pk_bf16_f32 v4, v8, v9
	s_waitcnt lgkmcnt(0)
	v_add_f32_e32 v0, v0, v1
	ds_bpermute_b32 v1, v181, v0
	v_cvt_pk_bf16_f32 v5, v10, v11
	global_store_dwordx4 v[24:25], v[2:5], off offset:256
	s_and_saveexec_b64 s[28:29], s[8:9]
	s_cbranch_execz .LBB0_560
	s_waitcnt lgkmcnt(0)
	v_add_f32_e32 v0, v0, v1
	v_fma_f32 v0, v0, s65, 0.5
	v_trunc_f32_e32 v0, v0
	v_mul_f32_e32 v1, 0x2f800000, v0
	v_floor_f32_e32 v1, v1
	v_fmac_f32_e32 v0, 0xcf800000, v1
	v_cvt_u32_f32_e32 v0, v0
	v_cvt_u32_f32_e32 v1, v1
	global_atomic_add_x2 v[112:113], v[0:1], off offset:1408
	s_branch .LBB0_560

.LBB0_656:
	v_lshl_add_u32 v140, s51, 8, v142
	v_ashrrev_i32_e32 v141, 31, v140
	v_lshl_add_u64 v[138:139], v[140:141], 3, s[16:17]
	global_load_dwordx2 v[146:147], v[138:139], off
	global_load_dwordx2 v[200:201], v[138:139], off offset:128
	global_load_dwordx2 v[202:203], v[138:139], off offset:256
	global_load_dwordx2 v[204:205], v[138:139], off offset:384
	global_load_dwordx2 v[206:207], v[138:139], off offset:1024
	global_load_dwordx2 v[208:209], v[138:139], off offset:1152
	global_load_dwordx2 v[210:211], v[138:139], off offset:1280
	global_load_dwordx2 v[212:213], v[138:139], off offset:1408
	v_max_f32_e32 v120, v120, v120
	v_max_f32_e32 v126, v126, v126
	v_max_f32_e32 v112, v112, v112
	v_max_f32_e32 v124, v124, v124
	v_max_f32_e32 v150, v116, v116
	v_max_f32_e32 v152, v118, v118
	v_max_f32_e32 v114, v114, v114
	v_max_f32_e32 v118, 0, v120
	v_max_f32_e32 v120, 0, v126
	v_max_f32_e32 v126, 0, v112
	v_max_f32_e32 v121, v121, v121
	v_max_f32_e32 v127, v127, v127
	v_max_f32_e32 v113, v113, v113
	v_max_f32_e32 v116, 0, v124
	v_max_f32_e32 v124, 0, v150
	v_max_f32_e32 v150, 0, v152
	v_max_f32_e32 v152, 0, v114
	v_max_f32_e32 v153, v119, v119
	v_max_f32_e32 v119, 0, v121
	v_max_f32_e32 v121, 0, v127
	v_max_f32_e32 v127, 0, v113
	v_lshl_or_b32 v148, s1, 8, v144
	v_max_f32_e32 v125, v125, v125
	v_max_f32_e32 v151, v117, v117
	v_max_f32_e32 v115, v115, v115
	v_ashrrev_i32_e32 v149, 31, v148
	v_max_f32_e32 v117, 0, v125
	v_max_f32_e32 v125, 0, v151
	v_max_f32_e32 v151, 0, v153
	v_max_f32_e32 v153, 0, v115
	v_max_f32_e32 v122, v122, v122
	v_max_f32_e32 v123, v123, v123
	v_max_f32_e32 v122, 0, v122
	v_max_f32_e32 v123, 0, v123
	v_max_f32_e32 v109, v109, v109
	v_max_f32_e32 v97, v97, v97
	v_max_f32_e32 v111, v111, v111
	v_max_f32_e32 v105, v105, v105
	v_max_f32_e32 v107, v107, v107
	v_max_f32_e32 v104, v104, v104
	v_max_f32_e32 v110, v110, v110
	v_max_f32_e32 v106, v106, v106
	v_max_f32_e32 v108, v108, v108
	v_max_f32_e32 v93, v93, v93
	v_max_f32_e32 v81, v81, v81
	v_max_f32_e32 v95, v95, v95
	v_max_f32_e32 v89, v89, v89
	v_max_f32_e32 v91, v91, v91
	v_max_f32_e32 v88, v88, v88
	v_max_f32_e32 v94, v94, v94
	v_max_f32_e32 v90, v90, v90
	v_max_f32_e32 v92, v92, v92
	v_max_f32_e32 v77, v77, v77
	v_max_f32_e32 v65, v65, v65
	v_max_f32_e32 v79, v79, v79
	v_max_f32_e32 v73, v73, v73
	v_max_f32_e32 v75, v75, v75
	v_max_f32_e32 v72, v72, v72
	v_max_f32_e32 v78, v78, v78
	v_max_f32_e32 v74, v74, v74
	v_max_f32_e32 v76, v76, v76
	v_max_f32_e32 v60, v60, v60
	v_max_f32_e32 v63, v63, v63
	v_max_f32_e32 v61, v61, v61
	v_max_f32_e32 v56, v56, v56
	v_max_f32_e32 v58, v58, v58
	v_max_f32_e32 v57, v57, v57
	v_max_f32_e32 v59, v59, v59
	v_max_f32_e32 v62, v62, v62
	s_mov_b32 s1, 0x100000
	v_max_f32_e32 v44, v44, v44
	v_max_f32_e32 v47, v47, v47
	v_max_f32_e32 v45, v45, v45
	v_max_f32_e32 v40, v40, v40
	v_max_f32_e32 v42, v42, v42
	v_max_f32_e32 v41, v41, v41
	v_max_f32_e32 v43, v43, v43
	v_max_f32_e32 v46, v46, v46
	v_max_f32_e32 v28, v28, v28
	s_waitcnt vmcnt(0)
	v_ffbh_u32_e32 v112, v147
	v_min_u32_e32 v114, 32, v112
	v_lshlrev_b64 v[112:113], v114, v[146:147]
	v_min_u32_e32 v112, 1, v112
	v_or_b32_e32 v112, v113, v112
	v_cvt_f32_u32_e32 v112, v112
	v_sub_u32_e32 v113, 32, v114
	v_lshlrev_b64 v[114:115], 1, v[148:149]
	v_max_f32_e32 v31, v31, v31
	v_ldexp_f32 v112, v112, v113
	v_mul_f32_e32 v112, 0x35800000, v112
	v_fmamk_f32 v112, v112, 0x3a800000, v182
	v_mul_f32_e32 v113, 0x4f800000, v112
	v_cmp_gt_f32_e32 vcc, s50, v112
	v_max_f32_e32 v29, v29, v29
	v_max_f32_e32 v24, v24, v24
	v_cndmask_b32_e32 v146, v112, v113, vcc
	v_sqrt_f32_e32 v147, v146
	v_lshlrev_b64 v[112:113], 13, v[140:141]
	v_lshl_add_u64 v[112:113], s[14:15], 0, v[112:113]
	v_lshl_add_u64 v[112:113], v[112:113], 0, v[114:115]
	v_add_u32_e32 v141, -1, v147
	v_add_u32_e32 v148, 1, v147
	v_fma_f32 v149, -v141, v147, v146
	v_fma_f32 v154, -v148, v147, v146
	v_cmp_ge_f32_e64 s[10:11], 0, v149
	v_max_f32_e32 v26, v26, v26
	v_max_f32_e32 v25, v25, v25
	v_cndmask_b32_e64 v141, v147, v141, s[10:11]
	v_cmp_lt_f32_e64 s[10:11], 0, v154
	v_max_f32_e32 v27, v27, v27
	v_max_f32_e32 v30, v30, v30
	v_cndmask_b32_e64 v141, v141, v148, s[10:11]
	v_mul_f32_e32 v147, 0x37800000, v141
	v_cndmask_b32_e32 v141, v141, v147, vcc
	v_cmp_class_f32_e32 vcc, v146, v183
	v_max_f32_e32 v13, v13, v13
	v_max_f32_e32 v8, v8, v8
	v_cndmask_b32_e32 v141, v141, v146, vcc
	v_div_scale_f32 v146, s[10:11], v141, v141, 1.0
	v_rcp_f32_e32 v147, v146
	v_div_scale_f32 v148, vcc, 1.0, v141, 1.0
	v_max_f32_e32 v14, v14, v14
	v_fma_f32 v149, -v146, v147, 1.0
	v_fmac_f32_e32 v147, v149, v147
	v_mul_f32_e32 v149, v148, v147
	v_fma_f32 v154, -v146, v149, v148
	v_fmac_f32_e32 v149, v154, v147
	v_fma_f32 v146, -v146, v149, v148
	v_div_fmas_f32 v146, v146, v147, v149
	v_div_fixup_f32 v146, v146, v141, 1.0
	v_pk_mul_f32 v[116:117], v[116:117], v[146:147] op_sel_hi:[1,0]
	v_pk_mul_f32 v[118:119], v[118:119], v[146:147] op_sel_hi:[1,0]
	v_pk_mul_f32 v[120:121], v[120:121], v[146:147] op_sel_hi:[1,0]
	v_pk_mul_f32 v[122:123], v[122:123], v[146:147] op_sel_hi:[1,0]
	v_pk_mul_f32 v[124:125], v[124:125], v[146:147] op_sel_hi:[1,0]
	v_pk_mul_f32 v[126:127], v[126:127], v[146:147] op_sel_hi:[1,0]
	v_pk_mul_f32 v[148:149], v[150:151], v[146:147] op_sel_hi:[1,0]
	v_pk_mul_f32 v[146:147], v[152:153], v[146:147] op_sel_hi:[1,0]
	v_pk_mul_f32 v[116:117], v[116:117], v[116:117]
	v_pk_mul_f32 v[118:119], v[118:119], v[118:119]
	v_pk_mul_f32 v[120:121], v[120:121], v[120:121]
	v_pk_mul_f32 v[122:123], v[122:123], v[122:123]
	v_pk_mul_f32 v[124:125], v[124:125], v[124:125]
	v_pk_mul_f32 v[126:127], v[126:127], v[126:127]
	v_pk_mul_f32 v[148:149], v[148:149], v[148:149]
	v_pk_mul_f32 v[146:147], v[146:147], v[146:147]
	v_cvt_pk_bf16_f32 v116, v116, v117
	v_cvt_pk_bf16_f32 v117, v120, v121
	v_cvt_pk_bf16_f32 v118, v118, v119
	v_cvt_pk_bf16_f32 v119, v122, v123
	v_cvt_pk_bf16_f32 v120, v124, v125
	v_cvt_pk_bf16_f32 v121, v148, v149
	v_cvt_pk_bf16_f32 v122, v126, v127
	v_cvt_pk_bf16_f32 v123, v146, v147
	global_store_dwordx4 v[112:113], v[116:119], off
	global_store_dwordx4 v[112:113], v[120:123], off offset:256
	s_nop 3
	v_max_f32_e32 v124, v99, v99
	v_max_f32_e32 v99, 0, v109
	v_max_f32_e32 v109, 0, v97
	v_max_f32_e32 v123, v103, v103
	v_max_f32_e32 v103, 0, v111
	v_max_f32_e32 v120, v101, v101
	v_max_f32_e32 v118, v100, v100
	v_max_f32_e32 v121, v102, v102
	v_max_f32_e32 v122, v98, v98
	v_max_f32_e32 v101, 0, v105
	v_max_f32_e32 v105, 0, v107
	v_max_f32_e32 v107, 0, v120
	v_max_f32_e32 v100, 0, v104
	v_max_f32_e32 v102, 0, v110
	v_max_f32_e32 v104, 0, v106
	v_max_f32_e32 v106, 0, v118
	v_max_f32_e32 v110, 0, v121
	v_max_f32_e32 v118, 0, v122
	v_max_f32_e32 v119, v96, v96
	v_or_b32_e32 v96, 16, v140
	v_max_f32_e32 v98, 0, v108
	v_max_f32_e32 v108, 0, v119
	v_max_f32_e32 v119, 0, v124
	v_max_f32_e32 v15, v15, v15
	v_max_f32_e32 v10, v10, v10
	v_max_f32_e32 v9, v9, v9
	v_max_f32_e32 v12, v12, v12
	v_max_f32_e32 v11, v11, v11
	v_readlane_b32 s62, v254, 61
	v_readlane_b32 s66, v254, 63
	v_readlane_b32 s63, v254, 62
	v_readlane_b32 s67, v255, 0
	v_ffbh_u32_e32 v97, v201
	v_min_u32_e32 v97, 32, v97
	v_lshlrev_b64 v[116:117], v97, v[200:201]
	v_min_u32_e32 v111, 1, v116
	v_or_b32_e32 v111, v117, v111
	v_cvt_f32_u32_e32 v116, v111
	v_sub_u32_e32 v97, 32, v97
	v_max_f32_e32 v111, 0, v123
	v_ldexp_f32 v97, v116, v97
	v_mul_f32_e32 v97, 0x35800000, v97
	v_fmamk_f32 v97, v97, 0x3a800000, v182
	v_mul_f32_e32 v116, 0x4f800000, v97
	v_cmp_gt_f32_e32 vcc, s50, v97
	s_nop 1
	v_cndmask_b32_e32 v116, v97, v116, vcc
	v_sqrt_f32_e32 v117, v116
	v_ashrrev_i32_e32 v97, 31, v96
	v_lshlrev_b64 v[96:97], 13, v[96:97]
	v_lshl_add_u64 v[96:97], s[14:15], 0, v[96:97]
	v_add_u32_e32 v120, -1, v117
	v_add_u32_e32 v121, 1, v117
	v_fma_f32 v122, -v120, v117, v116
	v_fma_f32 v123, -v121, v117, v116
	v_cmp_ge_f32_e64 s[10:11], 0, v122
	s_nop 1
	v_cndmask_b32_e64 v117, v117, v120, s[10:11]
	v_cmp_lt_f32_e64 s[10:11], 0, v123
	s_nop 1
	v_cndmask_b32_e64 v117, v117, v121, s[10:11]
	v_mul_f32_e32 v120, 0x37800000, v117
	v_cndmask_b32_e32 v117, v117, v120, vcc
	v_cmp_class_f32_e32 vcc, v116, v183
	s_nop 1
	v_cndmask_b32_e32 v120, v117, v116, vcc
	v_div_scale_f32 v121, s[10:11], v120, v120, 1.0
	v_rcp_f32_e32 v122, v121
	v_lshl_add_u64 v[116:117], v[96:97], 0, v[114:115]
	v_div_scale_f32 v96, vcc, 1.0, v120, 1.0
	v_fma_f32 v97, -v121, v122, 1.0
	v_fmac_f32_e32 v122, v97, v122
	v_mul_f32_e32 v97, v96, v122
	v_fma_f32 v123, -v121, v97, v96
	v_fmac_f32_e32 v97, v123, v122
	v_fma_f32 v96, -v121, v97, v96
	v_div_fmas_f32 v96, v96, v122, v97
	v_div_fixup_f32 v96, v96, v120, 1.0
	v_pk_mul_f32 v[98:99], v[98:99], v[96:97] op_sel_hi:[1,0]
	v_pk_mul_f32 v[100:101], v[100:101], v[96:97] op_sel_hi:[1,0]
	v_pk_mul_f32 v[102:103], v[102:103], v[96:97] op_sel_hi:[1,0]
	v_pk_mul_f32 v[104:105], v[104:105], v[96:97] op_sel_hi:[1,0]
	v_pk_mul_f32 v[106:107], v[106:107], v[96:97] op_sel_hi:[1,0]
	v_pk_mul_f32 v[108:109], v[108:109], v[96:97] op_sel_hi:[1,0]
	v_pk_mul_f32 v[110:111], v[110:111], v[96:97] op_sel_hi:[1,0]
	v_pk_mul_f32 v[96:97], v[118:119], v[96:97] op_sel_hi:[1,0]
	v_pk_mul_f32 v[98:99], v[98:99], v[98:99]
	v_pk_mul_f32 v[100:101], v[100:101], v[100:101]
	v_pk_mul_f32 v[102:103], v[102:103], v[102:103]
	v_pk_mul_f32 v[104:105], v[104:105], v[104:105]
	v_pk_mul_f32 v[106:107], v[106:107], v[106:107]
	v_pk_mul_f32 v[108:109], v[108:109], v[108:109]
	v_pk_mul_f32 v[110:111], v[110:111], v[110:111]
	v_pk_mul_f32 v[118:119], v[96:97], v[96:97]
	v_cvt_pk_bf16_f32 v96, v98, v99
	v_cvt_pk_bf16_f32 v97, v102, v103
	v_cvt_pk_bf16_f32 v98, v100, v101
	v_cvt_pk_bf16_f32 v99, v104, v105
	v_cvt_pk_bf16_f32 v100, v106, v107
	v_cvt_pk_bf16_f32 v101, v110, v111
	v_cvt_pk_bf16_f32 v102, v108, v109
	v_cvt_pk_bf16_f32 v103, v118, v119
	global_store_dwordx4 v[116:117], v[96:99], off
	global_store_dwordx4 v[116:117], v[100:103], off offset:256
	s_nop 3
	v_max_f32_e32 v104, v83, v83
	v_max_f32_e32 v83, 0, v93
	v_max_f32_e32 v93, 0, v81
	v_max_f32_e32 v103, v87, v87
	v_max_f32_e32 v87, 0, v95
	v_max_f32_e32 v100, v85, v85
	v_max_f32_e32 v98, v84, v84
	v_max_f32_e32 v101, v86, v86
	v_max_f32_e32 v102, v82, v82
	v_max_f32_e32 v85, 0, v89
	v_max_f32_e32 v89, 0, v91
	v_max_f32_e32 v91, 0, v100
	v_max_f32_e32 v84, 0, v88
	v_max_f32_e32 v86, 0, v94
	v_max_f32_e32 v88, 0, v90
	v_max_f32_e32 v90, 0, v98
	v_max_f32_e32 v94, 0, v101
	v_max_f32_e32 v98, 0, v102
	v_max_f32_e32 v99, v80, v80
	v_or_b32_e32 v80, 32, v140
	v_max_f32_e32 v82, 0, v92
	v_max_f32_e32 v92, 0, v99
	v_max_f32_e32 v99, 0, v104
	v_ffbh_u32_e32 v81, v203
	v_min_u32_e32 v81, 32, v81
	v_lshlrev_b64 v[96:97], v81, v[202:203]
	v_min_u32_e32 v95, 1, v96
	v_or_b32_e32 v95, v97, v95
	v_cvt_f32_u32_e32 v96, v95
	v_sub_u32_e32 v81, 32, v81
	v_max_f32_e32 v95, 0, v103
	v_ldexp_f32 v81, v96, v81
	v_mul_f32_e32 v81, 0x35800000, v81
	v_fmamk_f32 v81, v81, 0x3a800000, v182
	v_mul_f32_e32 v96, 0x4f800000, v81
	v_cmp_gt_f32_e32 vcc, s50, v81
	s_nop 1
	v_cndmask_b32_e32 v96, v81, v96, vcc
	v_sqrt_f32_e32 v97, v96
	v_ashrrev_i32_e32 v81, 31, v80
	v_lshlrev_b64 v[80:81], 13, v[80:81]
	v_lshl_add_u64 v[80:81], s[14:15], 0, v[80:81]
	v_add_u32_e32 v100, -1, v97
	v_add_u32_e32 v101, 1, v97
	v_fma_f32 v102, -v100, v97, v96
	v_fma_f32 v103, -v101, v97, v96
	v_cmp_ge_f32_e64 s[10:11], 0, v102
	s_nop 1
	v_cndmask_b32_e64 v97, v97, v100, s[10:11]
	v_cmp_lt_f32_e64 s[10:11], 0, v103
	s_nop 1
	v_cndmask_b32_e64 v97, v97, v101, s[10:11]
	v_mul_f32_e32 v100, 0x37800000, v97
	v_cndmask_b32_e32 v97, v97, v100, vcc
	v_cmp_class_f32_e32 vcc, v96, v183
	s_nop 1
	v_cndmask_b32_e32 v100, v97, v96, vcc
	v_div_scale_f32 v101, s[10:11], v100, v100, 1.0
	v_rcp_f32_e32 v102, v101
	v_lshl_add_u64 v[96:97], v[80:81], 0, v[114:115]
	v_div_scale_f32 v80, vcc, 1.0, v100, 1.0
	v_fma_f32 v81, -v101, v102, 1.0
	v_fmac_f32_e32 v102, v81, v102
	v_mul_f32_e32 v81, v80, v102
	v_fma_f32 v103, -v101, v81, v80
	v_fmac_f32_e32 v81, v103, v102
	v_fma_f32 v80, -v101, v81, v80
	v_div_fmas_f32 v80, v80, v102, v81
	v_div_fixup_f32 v80, v80, v100, 1.0
	v_pk_mul_f32 v[82:83], v[82:83], v[80:81] op_sel_hi:[1,0]
	v_pk_mul_f32 v[84:85], v[84:85], v[80:81] op_sel_hi:[1,0]
	v_pk_mul_f32 v[86:87], v[86:87], v[80:81] op_sel_hi:[1,0]
	v_pk_mul_f32 v[88:89], v[88:89], v[80:81] op_sel_hi:[1,0]
	v_pk_mul_f32 v[90:91], v[90:91], v[80:81] op_sel_hi:[1,0]
	v_pk_mul_f32 v[92:93], v[92:93], v[80:81] op_sel_hi:[1,0]
	v_pk_mul_f32 v[94:95], v[94:95], v[80:81] op_sel_hi:[1,0]
	v_pk_mul_f32 v[80:81], v[98:99], v[80:81] op_sel_hi:[1,0]
	v_pk_mul_f32 v[82:83], v[82:83], v[82:83]
	v_pk_mul_f32 v[84:85], v[84:85], v[84:85]
	v_pk_mul_f32 v[86:87], v[86:87], v[86:87]
	v_pk_mul_f32 v[88:89], v[88:89], v[88:89]
	v_pk_mul_f32 v[90:91], v[90:91], v[90:91]
	v_pk_mul_f32 v[92:93], v[92:93], v[92:93]
	v_pk_mul_f32 v[94:95], v[94:95], v[94:95]
	v_pk_mul_f32 v[98:99], v[80:81], v[80:81]
	v_cvt_pk_bf16_f32 v80, v82, v83
	v_cvt_pk_bf16_f32 v81, v86, v87
	v_cvt_pk_bf16_f32 v82, v84, v85
	v_cvt_pk_bf16_f32 v83, v88, v89
	v_cvt_pk_bf16_f32 v84, v90, v91
	v_cvt_pk_bf16_f32 v85, v94, v95
	v_cvt_pk_bf16_f32 v86, v92, v93
	v_cvt_pk_bf16_f32 v87, v98, v99
	global_store_dwordx4 v[96:97], v[80:83], off
	global_store_dwordx4 v[96:97], v[84:87], off offset:256
	s_nop 3
	v_max_f32_e32 v88, v67, v67
	v_max_f32_e32 v67, 0, v77
	v_max_f32_e32 v77, 0, v65
	v_max_f32_e32 v87, v71, v71
	v_max_f32_e32 v71, 0, v79
	v_max_f32_e32 v84, v69, v69
	v_max_f32_e32 v82, v68, v68
	v_max_f32_e32 v85, v70, v70
	v_max_f32_e32 v86, v66, v66
	v_max_f32_e32 v69, 0, v73
	v_max_f32_e32 v73, 0, v75
	v_max_f32_e32 v75, 0, v84
	v_max_f32_e32 v68, 0, v72
	v_max_f32_e32 v70, 0, v78
	v_max_f32_e32 v72, 0, v74
	v_max_f32_e32 v74, 0, v82
	v_max_f32_e32 v78, 0, v85
	v_max_f32_e32 v82, 0, v86
	v_max_f32_e32 v83, v64, v64
	v_or_b32_e32 v64, 48, v140
	v_max_f32_e32 v66, 0, v76
	v_max_f32_e32 v76, 0, v83
	v_max_f32_e32 v83, 0, v88
	v_ffbh_u32_e32 v65, v205
	v_min_u32_e32 v65, 32, v65
	v_lshlrev_b64 v[80:81], v65, v[204:205]
	v_min_u32_e32 v79, 1, v80
	v_or_b32_e32 v79, v81, v79
	v_cvt_f32_u32_e32 v80, v79
	v_sub_u32_e32 v65, 32, v65
	v_max_f32_e32 v79, 0, v87
	v_ldexp_f32 v65, v80, v65
	v_mul_f32_e32 v65, 0x35800000, v65
	v_fmamk_f32 v65, v65, 0x3a800000, v182
	v_mul_f32_e32 v80, 0x4f800000, v65
	v_cmp_gt_f32_e32 vcc, s50, v65
	s_nop 1
	v_cndmask_b32_e32 v80, v65, v80, vcc
	v_sqrt_f32_e32 v81, v80
	v_ashrrev_i32_e32 v65, 31, v64
	v_lshlrev_b64 v[64:65], 13, v[64:65]
	v_lshl_add_u64 v[64:65], s[14:15], 0, v[64:65]
	v_add_u32_e32 v84, -1, v81
	v_add_u32_e32 v85, 1, v81
	v_fma_f32 v86, -v84, v81, v80
	v_fma_f32 v87, -v85, v81, v80
	v_cmp_ge_f32_e64 s[10:11], 0, v86
	s_nop 1
	v_cndmask_b32_e64 v81, v81, v84, s[10:11]
	v_cmp_lt_f32_e64 s[10:11], 0, v87
	s_nop 1
	v_cndmask_b32_e64 v81, v81, v85, s[10:11]
	v_mul_f32_e32 v84, 0x37800000, v81
	v_cndmask_b32_e32 v81, v81, v84, vcc
	v_cmp_class_f32_e32 vcc, v80, v183
	s_nop 1
	v_cndmask_b32_e32 v84, v81, v80, vcc
	v_div_scale_f32 v85, s[10:11], v84, v84, 1.0
	v_rcp_f32_e32 v86, v85
	v_lshl_add_u64 v[80:81], v[64:65], 0, v[114:115]
	v_div_scale_f32 v64, vcc, 1.0, v84, 1.0
	v_fma_f32 v65, -v85, v86, 1.0
	v_fmac_f32_e32 v86, v65, v86
	v_mul_f32_e32 v65, v64, v86
	v_fma_f32 v87, -v85, v65, v64
	v_fmac_f32_e32 v65, v87, v86
	v_fma_f32 v64, -v85, v65, v64
	v_div_fmas_f32 v64, v64, v86, v65
	v_div_fixup_f32 v64, v64, v84, 1.0
	v_pk_mul_f32 v[66:67], v[66:67], v[64:65] op_sel_hi:[1,0]
	v_pk_mul_f32 v[68:69], v[68:69], v[64:65] op_sel_hi:[1,0]
	v_pk_mul_f32 v[70:71], v[70:71], v[64:65] op_sel_hi:[1,0]
	v_pk_mul_f32 v[72:73], v[72:73], v[64:65] op_sel_hi:[1,0]
	v_pk_mul_f32 v[74:75], v[74:75], v[64:65] op_sel_hi:[1,0]
	v_pk_mul_f32 v[76:77], v[76:77], v[64:65] op_sel_hi:[1,0]
	v_pk_mul_f32 v[78:79], v[78:79], v[64:65] op_sel_hi:[1,0]
	v_pk_mul_f32 v[64:65], v[82:83], v[64:65] op_sel_hi:[1,0]
	v_pk_mul_f32 v[66:67], v[66:67], v[66:67]
	v_pk_mul_f32 v[68:69], v[68:69], v[68:69]
	v_pk_mul_f32 v[70:71], v[70:71], v[70:71]
	v_pk_mul_f32 v[72:73], v[72:73], v[72:73]
	v_pk_mul_f32 v[74:75], v[74:75], v[74:75]
	v_pk_mul_f32 v[76:77], v[76:77], v[76:77]
	v_pk_mul_f32 v[78:79], v[78:79], v[78:79]
	v_pk_mul_f32 v[82:83], v[64:65], v[64:65]
	v_cvt_pk_bf16_f32 v64, v66, v67
	v_cvt_pk_bf16_f32 v65, v70, v71
	v_cvt_pk_bf16_f32 v66, v68, v69
	v_cvt_pk_bf16_f32 v67, v72, v73
	v_cvt_pk_bf16_f32 v68, v74, v75
	v_cvt_pk_bf16_f32 v69, v78, v79
	v_cvt_pk_bf16_f32 v70, v76, v77
	v_cvt_pk_bf16_f32 v71, v82, v83
	global_store_dwordx4 v[80:81], v[64:67], off
	global_store_dwordx4 v[80:81], v[68:71], off offset:256
	s_nop 3
	v_max_f32_e32 v67, v48, v48
	v_max_f32_e32 v48, 0, v60
	v_max_f32_e32 v68, v53, v53
	v_max_f32_e32 v53, 0, v63
	v_max_f32_e32 v69, v49, v49
	v_max_f32_e32 v49, 0, v61
	v_max_f32_e32 v66, v52, v52
	v_max_f32_e32 v71, v50, v50
	v_max_f32_e32 v50, 0, v56
	v_max_f32_e32 v56, 0, v66
	v_max_f32_e32 v70, v54, v54
	v_max_f32_e32 v54, 0, v58
	v_max_f32_e32 v58, 0, v67
	v_max_f32_e32 v73, v51, v51
	v_max_f32_e32 v51, 0, v57
	v_max_f32_e32 v57, 0, v68
	v_max_f32_e32 v72, v55, v55
	v_max_f32_e32 v55, 0, v59
	v_max_f32_e32 v59, 0, v69
	s_mov_b64 s[10:11], 0x100000
	v_max_f32_e32 v52, 0, v62
	v_max_f32_e32 v62, 0, v71
	v_ffbh_u32_e32 v60, v207
	v_min_u32_e32 v63, 32, v60
	v_lshlrev_b64 v[60:61], v63, v[206:207]
	v_min_u32_e32 v60, 1, v60
	v_or_b32_e32 v60, v61, v60
	v_cvt_f32_u32_e32 v61, v60
	v_sub_u32_e32 v63, 32, v63
	v_max_f32_e32 v60, 0, v70
	v_lshl_add_u64 v[64:65], v[112:113], 0, s[10:11]
	v_ldexp_f32 v61, v61, v63
	v_mul_f32_e32 v61, 0x35800000, v61
	v_fmamk_f32 v61, v61, 0x3a800000, v182
	v_mul_f32_e32 v63, 0x4f800000, v61
	v_cmp_gt_f32_e32 vcc, s50, v61
	s_nop 1
	v_cndmask_b32_e32 v66, v61, v63, vcc
	v_sqrt_f32_e32 v67, v66
	v_max_f32_e32 v61, 0, v72
	v_max_f32_e32 v63, 0, v73
	v_add_u32_e32 v68, -1, v67
	v_add_u32_e32 v69, 1, v67
	v_fma_f32 v70, -v68, v67, v66
	v_fma_f32 v71, -v69, v67, v66
	v_cmp_ge_f32_e64 s[10:11], 0, v70
	s_nop 1
	v_cndmask_b32_e64 v67, v67, v68, s[10:11]
	v_cmp_lt_f32_e64 s[10:11], 0, v71
	s_nop 1
	v_cndmask_b32_e64 v67, v67, v69, s[10:11]
	v_mul_f32_e32 v68, 0x37800000, v67
	v_cndmask_b32_e32 v67, v67, v68, vcc
	v_cmp_class_f32_e32 vcc, v66, v183
	s_nop 1
	v_cndmask_b32_e32 v68, v67, v66, vcc
	v_div_scale_f32 v69, s[10:11], v68, v68, 1.0
	v_rcp_f32_e32 v70, v69
	v_add_co_u32_e32 v66, vcc, s1, v112
	s_mov_b64 s[10:11], 0x120000
	s_nop 0
	v_addc_co_u32_e32 v67, vcc, 0, v113, vcc
	v_fma_f32 v72, -v69, v70, 1.0
	v_div_scale_f32 v71, vcc, 1.0, v68, 1.0
	v_fmac_f32_e32 v70, v72, v70
	v_mul_f32_e32 v72, v71, v70
	v_fma_f32 v73, -v69, v72, v71
	v_fmac_f32_e32 v72, v73, v70
	v_fma_f32 v69, -v69, v72, v71
	v_div_fmas_f32 v69, v69, v70, v72
	v_div_fixup_f32 v68, v69, v68, 1.0
	v_pk_mul_f32 v[48:49], v[48:49], v[68:69] op_sel_hi:[1,0]
	v_pk_mul_f32 v[50:51], v[50:51], v[68:69] op_sel_hi:[1,0]
	v_pk_mul_f32 v[52:53], v[52:53], v[68:69] op_sel_hi:[1,0]
	v_pk_mul_f32 v[54:55], v[54:55], v[68:69] op_sel_hi:[1,0]
	v_pk_mul_f32 v[56:57], v[56:57], v[68:69] op_sel_hi:[1,0]
	v_pk_mul_f32 v[58:59], v[58:59], v[68:69] op_sel_hi:[1,0]
	v_pk_mul_f32 v[60:61], v[60:61], v[68:69] op_sel_hi:[1,0]
	v_pk_mul_f32 v[62:63], v[62:63], v[68:69] op_sel_hi:[1,0]
	v_pk_mul_f32 v[48:49], v[48:49], v[48:49]
	v_pk_mul_f32 v[50:51], v[50:51], v[50:51]
	v_pk_mul_f32 v[52:53], v[52:53], v[52:53]
	v_pk_mul_f32 v[54:55], v[54:55], v[54:55]
	v_pk_mul_f32 v[56:57], v[56:57], v[56:57]
	v_pk_mul_f32 v[58:59], v[58:59], v[58:59]
	v_pk_mul_f32 v[60:61], v[60:61], v[60:61]
	v_pk_mul_f32 v[62:63], v[62:63], v[62:63]
	v_cvt_pk_bf16_f32 v48, v48, v49
	v_cvt_pk_bf16_f32 v49, v52, v53
	v_cvt_pk_bf16_f32 v50, v50, v51
	v_cvt_pk_bf16_f32 v51, v54, v55
	v_cvt_pk_bf16_f32 v52, v56, v57
	v_cvt_pk_bf16_f32 v53, v60, v61
	v_cvt_pk_bf16_f32 v54, v58, v59
	v_cvt_pk_bf16_f32 v55, v62, v63
	global_store_dwordx4 v[66:67], v[48:51], off
	global_store_dwordx4 v[64:65], v[52:55], off offset:256
	s_nop 3
	v_max_f32_e32 v51, v32, v32
	v_max_f32_e32 v32, 0, v44
	v_max_f32_e32 v52, v37, v37
	v_max_f32_e32 v37, 0, v47
	v_max_f32_e32 v53, v33, v33
	v_max_f32_e32 v33, 0, v45
	v_max_f32_e32 v50, v36, v36
	v_max_f32_e32 v55, v34, v34
	v_max_f32_e32 v34, 0, v40
	v_max_f32_e32 v40, 0, v50
	v_max_f32_e32 v54, v38, v38
	v_max_f32_e32 v38, 0, v42
	v_max_f32_e32 v42, 0, v51
	v_max_f32_e32 v57, v35, v35
	v_max_f32_e32 v35, 0, v41
	v_max_f32_e32 v41, 0, v52
	v_max_f32_e32 v56, v39, v39
	v_max_f32_e32 v39, 0, v43
	v_max_f32_e32 v43, 0, v53
	v_max_f32_e32 v36, 0, v46
	v_max_f32_e32 v46, 0, v55
	s_mov_b32 s1, 0x120000
	v_ffbh_u32_e32 v44, v209
	v_min_u32_e32 v47, 32, v44
	v_lshlrev_b64 v[44:45], v47, v[208:209]
	v_min_u32_e32 v44, 1, v44
	v_or_b32_e32 v44, v45, v44
	v_cvt_f32_u32_e32 v45, v44
	v_sub_u32_e32 v47, 32, v47
	v_max_f32_e32 v44, 0, v54
	v_lshl_add_u64 v[48:49], v[112:113], 0, s[10:11]
	v_ldexp_f32 v45, v45, v47
	v_mul_f32_e32 v45, 0x35800000, v45
	v_fmamk_f32 v45, v45, 0x3a800000, v182
	v_mul_f32_e32 v47, 0x4f800000, v45
	v_cmp_gt_f32_e32 vcc, s50, v45
	s_nop 1
	v_cndmask_b32_e32 v50, v45, v47, vcc
	v_sqrt_f32_e32 v51, v50
	v_max_f32_e32 v45, 0, v56
	v_max_f32_e32 v47, 0, v57
	v_add_u32_e32 v52, -1, v51
	v_add_u32_e32 v53, 1, v51
	v_fma_f32 v54, -v52, v51, v50
	v_fma_f32 v55, -v53, v51, v50
	v_cmp_ge_f32_e64 s[10:11], 0, v54
	s_nop 1
	v_cndmask_b32_e64 v51, v51, v52, s[10:11]
	v_cmp_lt_f32_e64 s[10:11], 0, v55
	s_nop 1
	v_cndmask_b32_e64 v51, v51, v53, s[10:11]
	v_mul_f32_e32 v52, 0x37800000, v51
	v_cndmask_b32_e32 v51, v51, v52, vcc
	v_cmp_class_f32_e32 vcc, v50, v183
	s_nop 1
	v_cndmask_b32_e32 v52, v51, v50, vcc
	v_div_scale_f32 v53, s[10:11], v52, v52, 1.0
	v_rcp_f32_e32 v54, v53
	v_add_co_u32_e32 v50, vcc, s1, v112
	s_mov_b64 s[10:11], 0x140000
	s_nop 0
	v_addc_co_u32_e32 v51, vcc, 0, v113, vcc
	v_fma_f32 v56, -v53, v54, 1.0
	v_div_scale_f32 v55, vcc, 1.0, v52, 1.0
	v_fmac_f32_e32 v54, v56, v54
	v_mul_f32_e32 v56, v55, v54
	v_fma_f32 v57, -v53, v56, v55
	v_fmac_f32_e32 v56, v57, v54
	v_fma_f32 v53, -v53, v56, v55
	v_div_fmas_f32 v53, v53, v54, v56
	v_div_fixup_f32 v52, v53, v52, 1.0
	v_pk_mul_f32 v[32:33], v[32:33], v[52:53] op_sel_hi:[1,0]
	v_pk_mul_f32 v[34:35], v[34:35], v[52:53] op_sel_hi:[1,0]
	v_pk_mul_f32 v[36:37], v[36:37], v[52:53] op_sel_hi:[1,0]
	v_pk_mul_f32 v[38:39], v[38:39], v[52:53] op_sel_hi:[1,0]
	v_pk_mul_f32 v[40:41], v[40:41], v[52:53] op_sel_hi:[1,0]
	v_pk_mul_f32 v[42:43], v[42:43], v[52:53] op_sel_hi:[1,0]
	v_pk_mul_f32 v[44:45], v[44:45], v[52:53] op_sel_hi:[1,0]
	v_pk_mul_f32 v[46:47], v[46:47], v[52:53] op_sel_hi:[1,0]
	v_pk_mul_f32 v[32:33], v[32:33], v[32:33]
	v_pk_mul_f32 v[34:35], v[34:35], v[34:35]
	v_pk_mul_f32 v[36:37], v[36:37], v[36:37]
	v_pk_mul_f32 v[38:39], v[38:39], v[38:39]
	v_pk_mul_f32 v[40:41], v[40:41], v[40:41]
	v_pk_mul_f32 v[42:43], v[42:43], v[42:43]
	v_pk_mul_f32 v[44:45], v[44:45], v[44:45]
	v_pk_mul_f32 v[46:47], v[46:47], v[46:47]
	v_cvt_pk_bf16_f32 v32, v32, v33
	v_cvt_pk_bf16_f32 v33, v36, v37
	v_cvt_pk_bf16_f32 v34, v34, v35
	v_cvt_pk_bf16_f32 v35, v38, v39
	v_cvt_pk_bf16_f32 v36, v40, v41
	v_cvt_pk_bf16_f32 v37, v44, v45
	v_cvt_pk_bf16_f32 v38, v42, v43
	v_cvt_pk_bf16_f32 v39, v46, v47
	global_store_dwordx4 v[50:51], v[32:35], off
	global_store_dwordx4 v[48:49], v[36:39], off offset:256
	s_nop 3
	v_max_f32_e32 v35, v16, v16
	v_max_f32_e32 v16, 0, v28
	v_max_f32_e32 v36, v21, v21
	v_max_f32_e32 v21, 0, v31
	v_max_f32_e32 v37, v17, v17
	v_max_f32_e32 v17, 0, v29
	v_max_f32_e32 v34, v20, v20
	v_max_f32_e32 v39, v18, v18
	v_max_f32_e32 v18, 0, v24
	v_max_f32_e32 v24, 0, v34
	v_max_f32_e32 v38, v22, v22
	v_max_f32_e32 v22, 0, v26
	v_max_f32_e32 v26, 0, v35
	v_max_f32_e32 v41, v19, v19
	v_max_f32_e32 v19, 0, v25
	v_max_f32_e32 v25, 0, v36
	v_max_f32_e32 v40, v23, v23
	v_max_f32_e32 v23, 0, v27
	v_max_f32_e32 v27, 0, v37
	v_max_f32_e32 v20, 0, v30
	v_max_f32_e32 v30, 0, v39
	s_mov_b32 s1, 0x140000
	v_ffbh_u32_e32 v28, v211
	v_min_u32_e32 v31, 32, v28
	v_lshlrev_b64 v[28:29], v31, v[210:211]
	v_min_u32_e32 v28, 1, v28
	v_or_b32_e32 v28, v29, v28
	v_cvt_f32_u32_e32 v29, v28
	v_sub_u32_e32 v31, 32, v31
	v_max_f32_e32 v28, 0, v38
	v_lshl_add_u64 v[32:33], v[112:113], 0, s[10:11]
	v_ldexp_f32 v29, v29, v31
	v_mul_f32_e32 v29, 0x35800000, v29
	v_fmamk_f32 v29, v29, 0x3a800000, v182
	v_mul_f32_e32 v31, 0x4f800000, v29
	v_cmp_gt_f32_e32 vcc, s50, v29
	s_nop 1
	v_cndmask_b32_e32 v34, v29, v31, vcc
	v_sqrt_f32_e32 v35, v34
	v_max_f32_e32 v29, 0, v40
	v_max_f32_e32 v31, 0, v41
	v_add_u32_e32 v36, -1, v35
	v_add_u32_e32 v37, 1, v35
	v_fma_f32 v38, -v36, v35, v34
	v_fma_f32 v39, -v37, v35, v34
	v_cmp_ge_f32_e64 s[10:11], 0, v38
	s_nop 1
	v_cndmask_b32_e64 v35, v35, v36, s[10:11]
	v_cmp_lt_f32_e64 s[10:11], 0, v39
	s_nop 1
	v_cndmask_b32_e64 v35, v35, v37, s[10:11]
	v_mul_f32_e32 v36, 0x37800000, v35
	v_cndmask_b32_e32 v35, v35, v36, vcc
	v_cmp_class_f32_e32 vcc, v34, v183
	s_nop 1
	v_cndmask_b32_e32 v36, v35, v34, vcc
	v_div_scale_f32 v37, s[10:11], v36, v36, 1.0
	v_rcp_f32_e32 v38, v37
	v_add_co_u32_e32 v34, vcc, s1, v112
	s_mov_b64 s[10:11], 0x160000
	s_nop 0
	v_addc_co_u32_e32 v35, vcc, 0, v113, vcc
	v_fma_f32 v40, -v37, v38, 1.0
	v_div_scale_f32 v39, vcc, 1.0, v36, 1.0
	v_fmac_f32_e32 v38, v40, v38
	v_mul_f32_e32 v40, v39, v38
	v_fma_f32 v41, -v37, v40, v39
	v_fmac_f32_e32 v40, v41, v38
	v_fma_f32 v37, -v37, v40, v39
	v_div_fmas_f32 v37, v37, v38, v40
	v_div_fixup_f32 v36, v37, v36, 1.0
	v_pk_mul_f32 v[16:17], v[16:17], v[36:37] op_sel_hi:[1,0]
	v_pk_mul_f32 v[18:19], v[18:19], v[36:37] op_sel_hi:[1,0]
	v_pk_mul_f32 v[20:21], v[20:21], v[36:37] op_sel_hi:[1,0]
	v_pk_mul_f32 v[22:23], v[22:23], v[36:37] op_sel_hi:[1,0]
	v_pk_mul_f32 v[24:25], v[24:25], v[36:37] op_sel_hi:[1,0]
	v_pk_mul_f32 v[26:27], v[26:27], v[36:37] op_sel_hi:[1,0]
	v_pk_mul_f32 v[28:29], v[28:29], v[36:37] op_sel_hi:[1,0]
	v_pk_mul_f32 v[30:31], v[30:31], v[36:37] op_sel_hi:[1,0]
	v_pk_mul_f32 v[16:17], v[16:17], v[16:17]
	v_pk_mul_f32 v[18:19], v[18:19], v[18:19]
	v_pk_mul_f32 v[20:21], v[20:21], v[20:21]
	v_pk_mul_f32 v[22:23], v[22:23], v[22:23]
	v_pk_mul_f32 v[24:25], v[24:25], v[24:25]
	v_pk_mul_f32 v[26:27], v[26:27], v[26:27]
	v_pk_mul_f32 v[28:29], v[28:29], v[28:29]
	v_pk_mul_f32 v[30:31], v[30:31], v[30:31]
	v_cvt_pk_bf16_f32 v16, v16, v17
	v_cvt_pk_bf16_f32 v17, v20, v21
	v_cvt_pk_bf16_f32 v18, v18, v19
	v_cvt_pk_bf16_f32 v19, v22, v23
	v_cvt_pk_bf16_f32 v20, v24, v25
	v_cvt_pk_bf16_f32 v21, v28, v29
	v_cvt_pk_bf16_f32 v22, v26, v27
	v_cvt_pk_bf16_f32 v23, v30, v31
	global_store_dwordx4 v[34:35], v[16:19], off
	global_store_dwordx4 v[32:33], v[20:23], off offset:256
	s_nop 3
	v_max_f32_e32 v18, v4, v4
	v_max_f32_e32 v21, v1, v1
	v_max_f32_e32 v1, 0, v13
	v_max_f32_e32 v23, v2, v2
	v_max_f32_e32 v2, 0, v8
	v_max_f32_e32 v8, 0, v18
	v_max_f32_e32 v20, v5, v5
	v_max_f32_e32 v4, 0, v14
	v_max_f32_e32 v5, 0, v15
	v_max_f32_e32 v19, v0, v0
	v_max_f32_e32 v22, v6, v6
	v_max_f32_e32 v6, 0, v10
	v_max_f32_e32 v10, 0, v19
	v_max_f32_e32 v25, v3, v3
	v_max_f32_e32 v3, 0, v9
	v_max_f32_e32 v9, 0, v20
	v_max_f32_e32 v24, v7, v7
	v_max_f32_e32 v0, 0, v12
	v_max_f32_e32 v7, 0, v11
	v_max_f32_e32 v11, 0, v21
	v_max_f32_e32 v12, 0, v22
	s_mov_b32 s1, 0x160000
	v_ffbh_u32_e32 v13, v213
	v_min_u32_e32 v18, 32, v13
	v_lshlrev_b64 v[14:15], v18, v[212:213]
	v_min_u32_e32 v13, 1, v14
	v_or_b32_e32 v13, v15, v13
	v_cvt_f32_u32_e32 v15, v13
	v_sub_u32_e32 v16, 32, v18
	v_max_f32_e32 v14, 0, v23
	v_max_f32_e32 v13, 0, v24
	v_ldexp_f32 v15, v15, v16
	v_mul_f32_e32 v15, 0x35800000, v15
	v_fmamk_f32 v15, v15, 0x3a800000, v182
	v_mul_f32_e32 v16, 0x4f800000, v15
	v_cmp_gt_f32_e32 vcc, s50, v15
	s_nop 1
	v_cndmask_b32_e32 v18, v15, v16, vcc
	v_sqrt_f32_e32 v19, v18
	v_lshl_add_u64 v[16:17], v[112:113], 0, s[10:11]
	v_max_f32_e32 v15, 0, v25
	v_add_u32_e32 v20, -1, v19
	v_add_u32_e32 v21, 1, v19
	v_fma_f32 v22, -v20, v19, v18
	v_fma_f32 v23, -v21, v19, v18
	v_cmp_ge_f32_e64 s[10:11], 0, v22
	s_nop 1
	v_cndmask_b32_e64 v19, v19, v20, s[10:11]
	v_cmp_lt_f32_e64 s[10:11], 0, v23
	s_nop 1
	v_cndmask_b32_e64 v19, v19, v21, s[10:11]
	v_mul_f32_e32 v20, 0x37800000, v19
	v_cndmask_b32_e32 v19, v19, v20, vcc
	v_cmp_class_f32_e32 vcc, v18, v183
	s_nop 1
	v_cndmask_b32_e32 v20, v19, v18, vcc
	v_div_scale_f32 v21, s[10:11], v20, v20, 1.0
	v_rcp_f32_e32 v22, v21
	v_add_co_u32_e32 v18, vcc, s1, v112
	v_fma_f32 v24, -v21, v22, 1.0
	s_nop 0
	v_addc_co_u32_e32 v19, vcc, 0, v113, vcc
	v_div_scale_f32 v23, vcc, 1.0, v20, 1.0
	v_fmac_f32_e32 v22, v24, v22
	v_mul_f32_e32 v24, v23, v22
	v_fma_f32 v25, -v21, v24, v23
	v_fmac_f32_e32 v24, v25, v22
	v_fma_f32 v21, -v21, v24, v23
	v_div_fmas_f32 v21, v21, v22, v24
	v_div_fixup_f32 v20, v21, v20, 1.0
	v_pk_mul_f32 v[0:1], v[0:1], v[20:21] op_sel_hi:[1,0]
	v_pk_mul_f32 v[2:3], v[2:3], v[20:21] op_sel_hi:[1,0]
	v_pk_mul_f32 v[4:5], v[4:5], v[20:21] op_sel_hi:[1,0]
	v_pk_mul_f32 v[6:7], v[6:7], v[20:21] op_sel_hi:[1,0]
	v_pk_mul_f32 v[8:9], v[8:9], v[20:21] op_sel_hi:[1,0]
	v_pk_mul_f32 v[10:11], v[10:11], v[20:21] op_sel_hi:[1,0]
	v_pk_mul_f32 v[12:13], v[12:13], v[20:21] op_sel_hi:[1,0]
	v_pk_mul_f32 v[14:15], v[14:15], v[20:21] op_sel_hi:[1,0]
	v_pk_mul_f32 v[0:1], v[0:1], v[0:1]
	v_pk_mul_f32 v[2:3], v[2:3], v[2:3]
	v_pk_mul_f32 v[4:5], v[4:5], v[4:5]
	v_pk_mul_f32 v[6:7], v[6:7], v[6:7]
	s_andn2_b64 vcc, exec, s[8:9]
	v_pk_mul_f32 v[8:9], v[8:9], v[8:9]
	v_pk_mul_f32 v[10:11], v[10:11], v[10:11]
	v_pk_mul_f32 v[12:13], v[12:13], v[12:13]
	v_pk_mul_f32 v[14:15], v[14:15], v[14:15]
	v_cvt_pk_bf16_f32 v0, v0, v1
	v_cvt_pk_bf16_f32 v1, v4, v5
	v_cvt_pk_bf16_f32 v2, v2, v3
	v_cvt_pk_bf16_f32 v3, v6, v7
	s_mov_b64 s[8:9], -1
	v_cvt_pk_bf16_f32 v4, v8, v9
	v_cvt_pk_bf16_f32 v5, v12, v13
	v_cvt_pk_bf16_f32 v6, v10, v11
	v_cvt_pk_bf16_f32 v7, v14, v15
	global_store_dwordx4 v[18:19], v[0:3], off
	global_store_dwordx4 v[16:17], v[4:7], off offset:256
	s_cbranch_vccnz .LBB0_645
	s_andn2_b64 vcc, exec, s[12:13]
	s_cbranch_vccnz .LBB0_644
	s_barrier
	s_branch .LBB0_644

.LBB0_725:
	s_add_u32 s26, s24, 0xfff00080
	s_addc_u32 s27, s25, -1
	s_add_i32 s63, s44, 0x120
	s_cmp_eq_u32 s62, 60
	s_cselect_b32 s29, s19, s27
	s_cselect_b32 s28, s58, s26
	s_cselect_b32 s27, s17, s61
	s_cselect_b32 s26, s59, s60
	s_add_i32 s68, s45, 0x120
	v_add_u32_e32 v154, s63, v147
	v_add_u32_e32 v158, s68, v147
	ds_read_b128 v[138:141], v154
	ds_read_b128 v[142:145], v154 offset:1024
	ds_read_b128 v[150:153], v154 offset:2048
	ds_read_b128 v[154:157], v154 offset:3072
	ds_read_b128 v[200:203], v158
	ds_read_b128 v[204:207], v158 offset:1024
	ds_read_b128 v[208:211], v158 offset:2048
	ds_read_b128 v[212:215], v158 offset:3072
	v_lshl_add_u64 v[158:159], s[24:25], 0, v[134:135]
	s_add_i32 m0, s43, 0xc000
	ds_read_b128 v[216:219], v149
	ds_read_b128 v[220:223], v149 offset:1024
	ds_read_b128 v[224:227], v149 offset:2048
	ds_read_b128 v[228:231], v149 offset:3072
	ds_read_b128 v[232:235], v149 offset:4096
	ds_read_b128 v[236:239], v149 offset:5120
	ds_read_b128 v[240:243], v149 offset:6144
	ds_read_b128 v[244:247], v149 offset:7168
	global_load_lds_dwordx4 v[158:159], off
	v_lshl_add_u64 v[158:159], s[24:25], 0, v[136:137]
	s_add_i32 m0, s43, 0xe000
	s_nop 0
	global_load_lds_dwordx4 v[158:159], off
	s_waitcnt vmcnt(8)
	s_waitcnt lgkmcnt(0)
	s_barrier
	s_setprio 1
	s_waitcnt lgkmcnt(0)
	v_mfma_f32_16x16x32_bf16 v[124:127], v[138:141], v[216:219], v[124:127]
	v_mfma_f32_16x16x32_bf16 v[120:123], v[150:153], v[216:219], v[120:123]
	v_mfma_f32_16x16x32_bf16 v[108:111], v[138:141], v[224:227], v[108:111]
	v_mfma_f32_16x16x32_bf16 v[104:107], v[150:153], v[224:227], v[104:107]
	v_mfma_f32_16x16x32_bf16 v[92:95], v[138:141], v[232:235], v[92:95]
	v_mfma_f32_16x16x32_bf16 v[88:91], v[150:153], v[232:235], v[88:91]
	v_mfma_f32_16x16x32_bf16 v[76:79], v[138:141], v[240:243], v[76:79]
	v_mfma_f32_16x16x32_bf16 v[72:75], v[150:153], v[240:243], v[72:75]
	v_mfma_f32_16x16x32_bf16 v[124:127], v[142:145], v[220:223], v[124:127]
	v_mfma_f32_16x16x32_bf16 v[120:123], v[154:157], v[220:223], v[120:123]
	v_mfma_f32_16x16x32_bf16 v[108:111], v[142:145], v[228:231], v[108:111]
	v_mfma_f32_16x16x32_bf16 v[104:107], v[154:157], v[228:231], v[104:107]
	v_mfma_f32_16x16x32_bf16 v[92:95], v[142:145], v[236:239], v[92:95]
	v_mfma_f32_16x16x32_bf16 v[88:91], v[154:157], v[236:239], v[88:91]
	v_mfma_f32_16x16x32_bf16 v[76:79], v[142:145], v[244:247], v[76:79]
	v_mfma_f32_16x16x32_bf16 v[72:75], v[154:157], v[244:247], v[72:75]
	s_setprio 0
	s_setprio 1
	v_mfma_f32_16x16x32_bf16 v[116:119], v[200:203], v[216:219], v[116:119]
	v_mfma_f32_16x16x32_bf16 v[112:115], v[208:211], v[216:219], v[112:115]
	v_mfma_f32_16x16x32_bf16 v[100:103], v[200:203], v[224:227], v[100:103]
	v_mfma_f32_16x16x32_bf16 v[96:99], v[208:211], v[224:227], v[96:99]
	v_mfma_f32_16x16x32_bf16 v[84:87], v[200:203], v[232:235], v[84:87]
	v_mfma_f32_16x16x32_bf16 v[80:83], v[208:211], v[232:235], v[80:83]
	v_mfma_f32_16x16x32_bf16 v[68:71], v[200:203], v[240:243], v[68:71]
	v_mfma_f32_16x16x32_bf16 v[64:67], v[208:211], v[240:243], v[64:67]
	v_mfma_f32_16x16x32_bf16 v[116:119], v[204:207], v[220:223], v[116:119]
	v_mfma_f32_16x16x32_bf16 v[112:115], v[212:215], v[220:223], v[112:115]
	v_mfma_f32_16x16x32_bf16 v[100:103], v[204:207], v[228:231], v[100:103]
	v_mfma_f32_16x16x32_bf16 v[96:99], v[212:215], v[228:231], v[96:99]
	v_mfma_f32_16x16x32_bf16 v[84:87], v[204:207], v[236:239], v[84:87]
	v_mfma_f32_16x16x32_bf16 v[80:83], v[212:215], v[236:239], v[80:83]
	v_mfma_f32_16x16x32_bf16 v[68:71], v[204:207], v[244:247], v[68:71]
	v_mfma_f32_16x16x32_bf16 v[64:67], v[212:215], v[244:247], v[64:67]
	s_setprio 0
	s_barrier
	s_add_i32 s63, s63, s42
	v_lshl_add_u64 v[158:159], s[26:27], 0, v[160:161]
	s_mov_b32 m0, s63
	ds_read_b128 v[216:219], v149 offset:16384
	ds_read_b128 v[220:223], v149 offset:17408
	ds_read_b128 v[224:227], v149 offset:18432
	ds_read_b128 v[228:231], v149 offset:19456
	ds_read_b128 v[232:235], v149 offset:20480
	ds_read_b128 v[236:239], v149 offset:21504
	ds_read_b128 v[240:243], v149 offset:22528
	ds_read_b128 v[244:247], v149 offset:23552
	global_load_lds_dwordx4 v[158:159], off
	s_add_i32 m0, s63, 0x2000
	s_add_u32 s66, s26, 0x100000
	v_lshl_add_u64 v[170:171], s[26:27], 0, v[128:129]
	s_addc_u32 s67, s27, 0
	s_add_i32 s63, s68, s42
	global_load_lds_dwordx4 v[170:171], off
	v_lshl_add_u64 v[174:175], s[66:67], 0, v[160:161]
	s_mov_b32 m0, s63
	v_lshl_add_u64 v[198:199], s[28:29], 0, v[130:131]
	global_load_lds_dwordx4 v[174:175], off
	v_lshl_add_u64 v[174:175], s[66:67], 0, v[128:129]
	s_add_i32 m0, s63, 0x2000
	s_nop 0
	global_load_lds_dwordx4 v[174:175], off
	v_lshl_add_u64 v[174:175], s[28:29], 0, v[132:133]
	s_mov_b32 m0, s43
	s_nop 0
	global_load_lds_dwordx4 v[174:175], off
	s_mov_b32 m0, s48
	s_nop 0
	global_load_lds_dwordx4 v[198:199], off
	s_waitcnt vmcnt(8)
	s_waitcnt lgkmcnt(0)
	s_barrier
	s_setprio 1
	s_waitcnt lgkmcnt(0)
	v_mfma_f32_16x16x32_bf16 v[60:63], v[138:141], v[216:219], v[60:63]
	v_mfma_f32_16x16x32_bf16 v[56:59], v[150:153], v[216:219], v[56:59]
	v_mfma_f32_16x16x32_bf16 v[44:47], v[138:141], v[224:227], v[44:47]
	v_mfma_f32_16x16x32_bf16 v[40:43], v[150:153], v[224:227], v[40:43]
	v_mfma_f32_16x16x32_bf16 v[28:31], v[138:141], v[232:235], v[28:31]
	v_mfma_f32_16x16x32_bf16 v[24:27], v[150:153], v[232:235], v[24:27]
	v_mfma_f32_16x16x32_bf16 v[12:15], v[138:141], v[240:243], v[12:15]
	v_mfma_f32_16x16x32_bf16 v[8:11], v[150:153], v[240:243], v[8:11]
	v_mfma_f32_16x16x32_bf16 v[60:63], v[142:145], v[220:223], v[60:63]
	v_mfma_f32_16x16x32_bf16 v[56:59], v[154:157], v[220:223], v[56:59]
	v_mfma_f32_16x16x32_bf16 v[44:47], v[142:145], v[228:231], v[44:47]
	v_mfma_f32_16x16x32_bf16 v[40:43], v[154:157], v[228:231], v[40:43]
	v_mfma_f32_16x16x32_bf16 v[28:31], v[142:145], v[236:239], v[28:31]
	v_mfma_f32_16x16x32_bf16 v[24:27], v[154:157], v[236:239], v[24:27]
	v_mfma_f32_16x16x32_bf16 v[12:15], v[142:145], v[244:247], v[12:15]
	v_mfma_f32_16x16x32_bf16 v[8:11], v[154:157], v[244:247], v[8:11]
	s_setprio 0
	s_setprio 1
	v_mfma_f32_16x16x32_bf16 v[52:55], v[200:203], v[216:219], v[52:55]
	v_mfma_f32_16x16x32_bf16 v[48:51], v[208:211], v[216:219], v[48:51]
	v_mfma_f32_16x16x32_bf16 v[36:39], v[200:203], v[224:227], v[36:39]
	v_mfma_f32_16x16x32_bf16 v[32:35], v[208:211], v[224:227], v[32:35]
	v_mfma_f32_16x16x32_bf16 v[20:23], v[200:203], v[232:235], v[20:23]
	v_mfma_f32_16x16x32_bf16 v[16:19], v[208:211], v[232:235], v[16:19]
	v_mfma_f32_16x16x32_bf16 v[4:7], v[200:203], v[240:243], v[4:7]
	v_mfma_f32_16x16x32_bf16 v[0:3], v[208:211], v[240:243], v[0:3]
	v_mfma_f32_16x16x32_bf16 v[52:55], v[204:207], v[220:223], v[52:55]
	v_mfma_f32_16x16x32_bf16 v[48:51], v[212:215], v[220:223], v[48:51]
	v_mfma_f32_16x16x32_bf16 v[36:39], v[204:207], v[228:231], v[36:39]
	v_mfma_f32_16x16x32_bf16 v[32:35], v[212:215], v[228:231], v[32:35]
	v_mfma_f32_16x16x32_bf16 v[20:23], v[204:207], v[236:239], v[20:23]
	v_mfma_f32_16x16x32_bf16 v[16:19], v[212:215], v[236:239], v[16:19]
	v_mfma_f32_16x16x32_bf16 v[4:7], v[204:207], v[244:247], v[4:7]
	v_mfma_f32_16x16x32_bf16 v[0:3], v[212:215], v[244:247], v[0:3]
	s_setprio 0
	s_barrier
	s_add_i32 s63, s46, 0x120
	s_add_i32 s66, s47, 0x120
	v_add_u32_e32 v154, s63, v147
	v_add_u32_e32 v172, s66, v147
	ds_read_b128 v[138:141], v154
	ds_read_b128 v[142:145], v154 offset:1024
	ds_read_b128 v[150:153], v154 offset:2048
	ds_read_b128 v[154:157], v154 offset:3072
	ds_read_b128 v[200:203], v172
	ds_read_b128 v[204:207], v172 offset:1024
	ds_read_b128 v[208:211], v172 offset:2048
	ds_read_b128 v[212:215], v172 offset:3072
	s_add_u32 s28, s28, 0x100000
	s_addc_u32 s29, s29, 0
	s_mov_b32 m0, s49
	v_lshl_add_u64 v[248:249], s[28:29], 0, v[132:133]
	ds_read_b128 v[216:219], v149 offset:32768
	ds_read_b128 v[220:223], v149 offset:33792
	ds_read_b128 v[224:227], v149 offset:34816
	ds_read_b128 v[228:231], v149 offset:35840
	ds_read_b128 v[232:235], v149 offset:36864
	ds_read_b128 v[236:239], v149 offset:37888
	ds_read_b128 v[240:243], v149 offset:38912
	ds_read_b128 v[244:247], v149 offset:39936
	global_load_lds_dwordx4 v[248:249], off
	v_lshl_add_u64 v[248:249], s[28:29], 0, v[130:131]
	s_mov_b32 m0, s52
	s_nop 0
	global_load_lds_dwordx4 v[248:249], off
	s_waitcnt vmcnt(8)
	s_waitcnt lgkmcnt(0)
	s_barrier
	s_setprio 1
	s_waitcnt lgkmcnt(0)
	v_mfma_f32_16x16x32_bf16 v[124:127], v[138:141], v[216:219], v[124:127]
	v_mfma_f32_16x16x32_bf16 v[120:123], v[150:153], v[216:219], v[120:123]
	v_mfma_f32_16x16x32_bf16 v[108:111], v[138:141], v[224:227], v[108:111]
	v_mfma_f32_16x16x32_bf16 v[104:107], v[150:153], v[224:227], v[104:107]
	v_mfma_f32_16x16x32_bf16 v[92:95], v[138:141], v[232:235], v[92:95]
	v_mfma_f32_16x16x32_bf16 v[88:91], v[150:153], v[232:235], v[88:91]
	v_mfma_f32_16x16x32_bf16 v[76:79], v[138:141], v[240:243], v[76:79]
	v_mfma_f32_16x16x32_bf16 v[72:75], v[150:153], v[240:243], v[72:75]
	v_mfma_f32_16x16x32_bf16 v[124:127], v[142:145], v[220:223], v[124:127]
	v_mfma_f32_16x16x32_bf16 v[120:123], v[154:157], v[220:223], v[120:123]
	v_mfma_f32_16x16x32_bf16 v[108:111], v[142:145], v[228:231], v[108:111]
	v_mfma_f32_16x16x32_bf16 v[104:107], v[154:157], v[228:231], v[104:107]
	v_mfma_f32_16x16x32_bf16 v[92:95], v[142:145], v[236:239], v[92:95]
	v_mfma_f32_16x16x32_bf16 v[88:91], v[154:157], v[236:239], v[88:91]
	v_mfma_f32_16x16x32_bf16 v[76:79], v[142:145], v[244:247], v[76:79]
	v_mfma_f32_16x16x32_bf16 v[72:75], v[154:157], v[244:247], v[72:75]
	s_setprio 0
	s_setprio 1
	v_mfma_f32_16x16x32_bf16 v[116:119], v[200:203], v[216:219], v[116:119]
	v_mfma_f32_16x16x32_bf16 v[112:115], v[208:211], v[216:219], v[112:115]
	v_mfma_f32_16x16x32_bf16 v[100:103], v[200:203], v[224:227], v[100:103]
	v_mfma_f32_16x16x32_bf16 v[96:99], v[208:211], v[224:227], v[96:99]
	v_mfma_f32_16x16x32_bf16 v[84:87], v[200:203], v[232:235], v[84:87]
	v_mfma_f32_16x16x32_bf16 v[80:83], v[208:211], v[232:235], v[80:83]
	v_mfma_f32_16x16x32_bf16 v[68:71], v[200:203], v[240:243], v[68:71]
	v_mfma_f32_16x16x32_bf16 v[64:67], v[208:211], v[240:243], v[64:67]
	v_mfma_f32_16x16x32_bf16 v[116:119], v[204:207], v[220:223], v[116:119]
	v_mfma_f32_16x16x32_bf16 v[112:115], v[212:215], v[220:223], v[112:115]
	v_mfma_f32_16x16x32_bf16 v[100:103], v[204:207], v[228:231], v[100:103]
	v_mfma_f32_16x16x32_bf16 v[96:99], v[212:215], v[228:231], v[96:99]
	v_mfma_f32_16x16x32_bf16 v[84:87], v[204:207], v[236:239], v[84:87]
	v_mfma_f32_16x16x32_bf16 v[80:83], v[212:215], v[236:239], v[80:83]
	v_mfma_f32_16x16x32_bf16 v[68:71], v[204:207], v[244:247], v[68:71]
	v_mfma_f32_16x16x32_bf16 v[64:67], v[212:215], v[244:247], v[64:67]
	s_setprio 0
	s_barrier
	s_add_i32 s28, s63, s42
	v_lshl_add_u64 v[158:159], v[158:159], 0, s[88:89]
	s_mov_b32 m0, s28
	ds_read_b128 v[216:219], v149 offset:49152
	ds_read_b128 v[220:223], v149 offset:50176
	ds_read_b128 v[224:227], v149 offset:51200
	ds_read_b128 v[228:231], v149 offset:52224
	ds_read_b128 v[232:235], v149 offset:53248
	ds_read_b128 v[236:239], v149 offset:54272
	ds_read_b128 v[240:243], v149 offset:55296
	ds_read_b128 v[244:247], v149 offset:56320
	global_load_lds_dwordx4 v[158:159], off
	s_add_i32 m0, s28, 0x2000
	s_add_u32 s26, s26, 0x100080
	v_lshl_add_u64 v[158:159], v[170:171], 0, s[88:89]
	s_addc_u32 s27, s27, 0
	s_add_i32 s28, s66, s42
	global_load_lds_dwordx4 v[158:159], off
	v_lshl_add_u64 v[158:159], s[26:27], 0, v[160:161]
	s_mov_b32 m0, s28
	s_nop 0
	global_load_lds_dwordx4 v[158:159], off
	v_lshl_add_u64 v[158:159], s[26:27], 0, v[128:129]
	s_add_i32 m0, s28, 0x2000
	s_nop 0
	global_load_lds_dwordx4 v[158:159], off
	v_lshl_add_u64 v[158:159], v[174:175], 0, s[88:89]
	s_mov_b32 m0, s53
	s_nop 0
	global_load_lds_dwordx4 v[158:159], off
	v_lshl_add_u64 v[158:159], v[198:199], 0, s[88:89]
	s_mov_b32 m0, s56
	s_nop 0
	global_load_lds_dwordx4 v[158:159], off
	s_waitcnt vmcnt(8)
	s_waitcnt lgkmcnt(0)
	s_barrier
	s_setprio 1
	s_waitcnt lgkmcnt(0)
	v_mfma_f32_16x16x32_bf16 v[60:63], v[138:141], v[216:219], v[60:63]
	v_mfma_f32_16x16x32_bf16 v[56:59], v[150:153], v[216:219], v[56:59]
	v_mfma_f32_16x16x32_bf16 v[44:47], v[138:141], v[224:227], v[44:47]
	v_mfma_f32_16x16x32_bf16 v[40:43], v[150:153], v[224:227], v[40:43]
	v_mfma_f32_16x16x32_bf16 v[28:31], v[138:141], v[232:235], v[28:31]
	v_mfma_f32_16x16x32_bf16 v[24:27], v[150:153], v[232:235], v[24:27]
	v_mfma_f32_16x16x32_bf16 v[12:15], v[138:141], v[240:243], v[12:15]
	v_mfma_f32_16x16x32_bf16 v[8:11], v[150:153], v[240:243], v[8:11]
	v_mfma_f32_16x16x32_bf16 v[60:63], v[142:145], v[220:223], v[60:63]
	v_mfma_f32_16x16x32_bf16 v[56:59], v[154:157], v[220:223], v[56:59]
	v_mfma_f32_16x16x32_bf16 v[44:47], v[142:145], v[228:231], v[44:47]
	v_mfma_f32_16x16x32_bf16 v[40:43], v[154:157], v[228:231], v[40:43]
	v_mfma_f32_16x16x32_bf16 v[28:31], v[142:145], v[236:239], v[28:31]
	v_mfma_f32_16x16x32_bf16 v[24:27], v[154:157], v[236:239], v[24:27]
	v_mfma_f32_16x16x32_bf16 v[12:15], v[142:145], v[244:247], v[12:15]
	v_mfma_f32_16x16x32_bf16 v[8:11], v[154:157], v[244:247], v[8:11]
	s_setprio 0
	s_setprio 1
	v_mfma_f32_16x16x32_bf16 v[52:55], v[200:203], v[216:219], v[52:55]
	v_mfma_f32_16x16x32_bf16 v[48:51], v[208:211], v[216:219], v[48:51]
	v_mfma_f32_16x16x32_bf16 v[36:39], v[200:203], v[224:227], v[36:39]
	v_mfma_f32_16x16x32_bf16 v[32:35], v[208:211], v[224:227], v[32:35]
	v_mfma_f32_16x16x32_bf16 v[20:23], v[200:203], v[232:235], v[20:23]
	v_mfma_f32_16x16x32_bf16 v[16:19], v[208:211], v[232:235], v[16:19]
	v_mfma_f32_16x16x32_bf16 v[4:7], v[200:203], v[240:243], v[4:7]
	v_mfma_f32_16x16x32_bf16 v[0:3], v[208:211], v[240:243], v[0:3]
	v_mfma_f32_16x16x32_bf16 v[52:55], v[204:207], v[220:223], v[52:55]
	v_mfma_f32_16x16x32_bf16 v[48:51], v[212:215], v[220:223], v[48:51]
	v_mfma_f32_16x16x32_bf16 v[36:39], v[204:207], v[228:231], v[36:39]
	v_mfma_f32_16x16x32_bf16 v[32:35], v[212:215], v[228:231], v[32:35]
	v_mfma_f32_16x16x32_bf16 v[20:23], v[204:207], v[236:239], v[20:23]
	v_mfma_f32_16x16x32_bf16 v[16:19], v[212:215], v[236:239], v[16:19]
	v_mfma_f32_16x16x32_bf16 v[4:7], v[204:207], v[244:247], v[4:7]
	v_mfma_f32_16x16x32_bf16 v[0:3], v[212:215], v[244:247], v[0:3]
	s_setprio 0
	s_barrier
	s_add_i32 s62, s62, 2
	s_add_u32 s24, s24, 0x100
	s_addc_u32 s25, s25, 0
	s_add_u32 s60, s60, 0x100
	s_addc_u32 s61, s61, 0
	s_cmp_gt_u32 s62, 61
	s_cbranch_scc0 .LBB0_725
	v_lshl_add_u32 v138, s51, 8, v146
	v_lshl_or_b32 v142, s1, 8, v148
	v_ashrrev_i32_e32 v139, 31, v138
	v_ashrrev_i32_e32 v143, 31, v142
	v_lshlrev_b64 v[140:141], 10, v[138:139]
	v_lshl_add_u64 v[140:141], v[140:141], 0, v[142:143]
	v_lshl_add_u64 v[144:145], v[140:141], 2, s[12:13]
	v_mov_b32_e32 v248, v144
	v_mov_b32_e32 v249, v145
	global_load_dwordx4 v[200:203], v[248:249], off
	global_load_dwordx4 v[204:207], v[248:249], off offset:16
	global_load_dwordx4 v[208:211], v[248:249], off offset:512
	global_load_dwordx4 v[212:215], v[248:249], off offset:528
	s_mov_b64 s[98:99], 0x10000
	v_lshl_add_u64 v[250:251], v[248:249], 0, s[98:99]
	global_load_dwordx4 v[216:219], v[250:251], off
	global_load_dwordx4 v[220:223], v[250:251], off offset:16
	global_load_dwordx4 v[224:227], v[250:251], off offset:512
	global_load_dwordx4 v[228:231], v[250:251], off offset:528
	s_mov_b64 s[98:99], 0x20000
	v_lshl_add_u64 v[250:251], v[248:249], 0, s[98:99]
	global_load_dwordx4 v[232:235], v[250:251], off
	global_load_dwordx4 v[236:239], v[250:251], off offset:16
	global_load_dwordx4 v[240:243], v[250:251], off offset:512
	global_load_dwordx4 v[244:247], v[250:251], off offset:528
	s_waitcnt vmcnt(8)
	s_nop 1
	s_nop 1
	s_mov_b64 s[24:25], -1
	s_and_b64 vcc, exec, s[4:5]
	v_pk_add_f32 v[126:127], v[126:127], v[202:203]
	v_pk_add_f32 v[124:125], v[124:125], v[200:201]
	v_pk_add_f32 v[122:123], v[122:123], v[206:207]
	v_pk_add_f32 v[120:121], v[120:121], v[204:205]
	global_store_dwordx4 v[144:145], v[124:127], off
	global_store_dwordx4 v[144:145], v[120:123], off offset:16
	s_cbranch_vccz .LBB0_728
	s_nop 1
	s_nop 1
	s_mov_b64 s[24:25], 0
	v_pk_add_f32 v[152:153], v[118:119], v[210:211]
	v_pk_add_f32 v[150:151], v[116:117], v[208:209]
	v_pk_add_f32 v[156:157], v[114:115], v[214:215]
	v_pk_add_f32 v[154:155], v[112:113], v[212:213]
	global_store_dwordx4 v[144:145], v[150:153], off offset:512
	global_store_dwordx4 v[144:145], v[154:157], off offset:528
.LBB0_728:
	s_andn2_b64 vcc, exec, s[24:25]
	s_cbranch_vccnz .LBB0_732
	v_cvt_pk_bf16_f32 v150, v124, v125
	v_mul_f32_e32 v125, v125, v125
	v_fmac_f32_e32 v125, v124, v124
	v_mul_f32_e32 v124, v127, v127
	v_cvt_pk_bf16_f32 v152, v120, v121
	v_fmac_f32_e32 v124, v126, v126
	v_mul_f32_e32 v121, v121, v121
	v_add_f32_e32 v124, v125, v124
	v_fmac_f32_e32 v121, v120, v120
	v_cvt_pk_bf16_f32 v151, v126, v127
	v_cvt_pk_bf16_f32 v153, v122, v123
	v_lshl_add_u64 v[154:155], v[140:141], 1, s[10:11]
	v_add_f32_e32 v120, v124, v121
	v_mul_f32_e32 v121, v123, v123
	global_store_dwordx4 v[154:155], v[150:153], off
	v_fmac_f32_e32 v121, v122, v122
	s_nop 0
	v_add_f32_e32 v150, v121, v120
	s_nop 1
	s_nop 1
	v_pk_add_f32 v[114:115], v[114:115], v[214:215]
	v_pk_add_f32 v[118:119], v[118:119], v[210:211]
	v_pk_add_f32 v[116:117], v[116:117], v[208:209]
	v_pk_add_f32 v[112:113], v[112:113], v[212:213]
	global_store_dwordx4 v[144:145], v[116:119], off offset:512
	global_store_dwordx4 v[144:145], v[112:115], off offset:528
	v_cvt_pk_bf16_f32 v123, v114, v115
	v_cvt_pk_bf16_f32 v120, v116, v117
	v_mul_f32_e32 v115, v115, v115
	v_fmac_f32_e32 v115, v114, v114
	v_mul_f32_e32 v114, v117, v117
	v_fmac_f32_e32 v114, v116, v116
	v_mul_f32_e32 v116, v119, v119
	v_cvt_pk_bf16_f32 v122, v112, v113
	v_fmac_f32_e32 v116, v118, v118
	v_mul_f32_e32 v113, v113, v113
	v_add_f32_e32 v114, v114, v116
	v_fmac_f32_e32 v113, v112, v112
	v_add_f32_e32 v112, v114, v113
	v_add_f32_e32 v112, v115, v112
	v_add_f32_e32 v112, v150, v112
	ds_bpermute_b32 v113, v180, v112
	v_cvt_pk_bf16_f32 v121, v118, v119
	global_store_dwordx4 v[154:155], v[120:123], off offset:256
	s_waitcnt lgkmcnt(0)
	v_add_f32_e32 v112, v112, v113
	ds_bpermute_b32 v113, v181, v112
	s_and_saveexec_b64 s[24:25], s[6:7]
	s_cbranch_execz .LBB0_731
	s_waitcnt lgkmcnt(0)
	v_add_f32_e32 v112, v112, v113
	v_fma_f32 v112, v112, s65, 0.5
	v_trunc_f32_e32 v112, v112
	v_mul_f32_e32 v113, 0x2f800000, v112
	v_floor_f32_e32 v113, v113
	v_fmac_f32_e32 v112, 0xcf800000, v113
	v_cvt_u32_f32_e32 v112, v112
	v_cvt_u32_f32_e32 v113, v113
	v_lshl_add_u64 v[114:115], v[138:139], 3, s[14:15]
	global_atomic_add_x2 v[114:115], v[112:113], off

.LBB0_732:
	v_or_b32_e32 v112, 16, v138
	s_waitcnt lgkmcnt(0)
	v_ashrrev_i32_e32 v113, 31, v112
	v_lshlrev_b64 v[112:113], 10, v[112:113]
	v_lshl_add_u64 v[114:115], v[112:113], 0, v[142:143]
	v_lshl_add_u64 v[112:113], v[114:115], 2, s[12:13]
	s_mov_b64 s[98:99], 0x30000
	v_lshl_add_u64 v[250:251], v[248:249], 0, s[98:99]
	global_load_dwordx4 v[200:203], v[250:251], off
	global_load_dwordx4 v[204:207], v[250:251], off offset:16
	global_load_dwordx4 v[208:211], v[250:251], off offset:512
	global_load_dwordx4 v[212:215], v[250:251], off offset:528
	s_waitcnt vmcnt(12)
	s_nop 1
	s_nop 1
	s_mov_b64 s[24:25], -1
	s_and_b64 vcc, exec, s[4:5]
	v_pk_add_f32 v[110:111], v[110:111], v[218:219]
	v_pk_add_f32 v[108:109], v[108:109], v[216:217]
	v_pk_add_f32 v[106:107], v[106:107], v[222:223]
	v_pk_add_f32 v[104:105], v[104:105], v[220:221]
	global_store_dwordx4 v[112:113], v[108:111], off
	global_store_dwordx4 v[112:113], v[104:107], off offset:16
	s_cbranch_vccz .LBB0_734
	s_nop 1
	s_nop 1
	s_mov_b64 s[24:25], 0
	v_pk_add_f32 v[118:119], v[102:103], v[226:227]
	v_pk_add_f32 v[116:117], v[100:101], v[224:225]
	v_pk_add_f32 v[122:123], v[98:99], v[230:231]
	v_pk_add_f32 v[120:121], v[96:97], v[228:229]
	global_store_dwordx4 v[112:113], v[116:119], off offset:512
	global_store_dwordx4 v[112:113], v[120:123], off offset:528
.LBB0_734:
	v_readlane_b32 s62, v254, 61
	v_readlane_b32 s66, v254, 63
	s_andn2_b64 vcc, exec, s[24:25]
	v_readlane_b32 s63, v254, 62
	v_readlane_b32 s67, v255, 0
	s_cbranch_vccnz .LBB0_738
	v_cvt_pk_bf16_f32 v116, v108, v109
	v_mul_f32_e32 v109, v109, v109
	v_fmac_f32_e32 v109, v108, v108
	v_mul_f32_e32 v108, v111, v111
	v_cvt_pk_bf16_f32 v118, v104, v105
	v_fmac_f32_e32 v108, v110, v110
	v_mul_f32_e32 v105, v105, v105
	v_add_f32_e32 v108, v109, v108
	v_fmac_f32_e32 v105, v104, v104
	v_cvt_pk_bf16_f32 v117, v110, v111
	v_cvt_pk_bf16_f32 v119, v106, v107
	v_lshl_add_u64 v[114:115], v[114:115], 1, s[10:11]
	v_add_f32_e32 v104, v108, v105
	v_mul_f32_e32 v105, v107, v107
	global_store_dwordx4 v[114:115], v[116:119], off
	v_fmac_f32_e32 v105, v106, v106
	s_nop 0
	v_add_f32_e32 v116, v105, v104
	s_nop 1
	s_nop 1
	v_pk_add_f32 v[98:99], v[98:99], v[230:231]
	v_pk_add_f32 v[102:103], v[102:103], v[226:227]
	v_pk_add_f32 v[100:101], v[100:101], v[224:225]
	v_pk_add_f32 v[96:97], v[96:97], v[228:229]
	global_store_dwordx4 v[112:113], v[100:103], off offset:512
	global_store_dwordx4 v[112:113], v[96:99], off offset:528
	v_cvt_pk_bf16_f32 v107, v98, v99
	v_cvt_pk_bf16_f32 v104, v100, v101
	v_mul_f32_e32 v99, v99, v99
	v_fmac_f32_e32 v99, v98, v98
	v_mul_f32_e32 v98, v101, v101
	v_fmac_f32_e32 v98, v100, v100
	v_mul_f32_e32 v100, v103, v103
	v_cvt_pk_bf16_f32 v106, v96, v97
	v_fmac_f32_e32 v100, v102, v102
	v_mul_f32_e32 v97, v97, v97
	v_add_f32_e32 v98, v98, v100
	v_fmac_f32_e32 v97, v96, v96
	v_add_f32_e32 v96, v98, v97
	v_add_f32_e32 v96, v99, v96
	v_add_f32_e32 v96, v116, v96
	ds_bpermute_b32 v97, v180, v96
	v_cvt_pk_bf16_f32 v105, v102, v103
	global_store_dwordx4 v[114:115], v[104:107], off offset:256
	s_waitcnt lgkmcnt(0)
	v_add_f32_e32 v96, v96, v97
	ds_bpermute_b32 v97, v181, v96
	s_and_saveexec_b64 s[24:25], s[6:7]
	s_cbranch_execz .LBB0_737
	s_waitcnt lgkmcnt(0)
	v_add_f32_e32 v96, v96, v97
	v_fma_f32 v96, v96, s65, 0.5
	v_trunc_f32_e32 v96, v96
	v_mul_f32_e32 v97, 0x2f800000, v96
	v_floor_f32_e32 v97, v97
	v_fmac_f32_e32 v96, 0xcf800000, v97
	v_cvt_u32_f32_e32 v96, v96
	v_cvt_u32_f32_e32 v97, v97
	v_lshl_add_u64 v[98:99], v[138:139], 3, s[14:15]
	global_atomic_add_x2 v[98:99], v[96:97], off offset:128

.LBB0_738:
	v_or_b32_e32 v96, 32, v138
	s_waitcnt lgkmcnt(0)
	v_ashrrev_i32_e32 v97, 31, v96
	v_lshlrev_b64 v[96:97], 10, v[96:97]
	v_lshl_add_u64 v[98:99], v[96:97], 0, v[142:143]
	v_lshl_add_u64 v[96:97], v[98:99], 2, s[12:13]
	s_mov_b64 s[98:99], 0x80000
	v_lshl_add_u64 v[250:251], v[248:249], 0, s[98:99]
	global_load_dwordx4 v[216:219], v[250:251], off
	global_load_dwordx4 v[220:223], v[250:251], off offset:16
	global_load_dwordx4 v[224:227], v[250:251], off offset:512
	global_load_dwordx4 v[228:231], v[250:251], off offset:528
	s_waitcnt vmcnt(16)
	s_nop 1
	s_nop 1
	s_mov_b64 s[24:25], -1
	s_and_b64 vcc, exec, s[4:5]
	v_pk_add_f32 v[94:95], v[94:95], v[234:235]
	v_pk_add_f32 v[92:93], v[92:93], v[232:233]
	v_pk_add_f32 v[90:91], v[90:91], v[238:239]
	v_pk_add_f32 v[88:89], v[88:89], v[236:237]
	global_store_dwordx4 v[96:97], v[92:95], off
	global_store_dwordx4 v[96:97], v[88:91], off offset:16
	s_cbranch_vccz .LBB0_740
	s_nop 1
	s_nop 1
	s_mov_b64 s[24:25], 0
	v_pk_add_f32 v[102:103], v[86:87], v[242:243]
	v_pk_add_f32 v[100:101], v[84:85], v[240:241]
	v_pk_add_f32 v[106:107], v[82:83], v[246:247]
	v_pk_add_f32 v[104:105], v[80:81], v[244:245]
	global_store_dwordx4 v[96:97], v[100:103], off offset:512
	global_store_dwordx4 v[96:97], v[104:107], off offset:528
.LBB0_740:
	s_andn2_b64 vcc, exec, s[24:25]
	s_cbranch_vccnz .LBB0_744
	v_cvt_pk_bf16_f32 v100, v92, v93
	v_mul_f32_e32 v93, v93, v93
	v_fmac_f32_e32 v93, v92, v92
	v_mul_f32_e32 v92, v95, v95
	v_cvt_pk_bf16_f32 v102, v88, v89
	v_fmac_f32_e32 v92, v94, v94
	v_mul_f32_e32 v89, v89, v89
	v_add_f32_e32 v92, v93, v92
	v_fmac_f32_e32 v89, v88, v88
	v_cvt_pk_bf16_f32 v101, v94, v95
	v_cvt_pk_bf16_f32 v103, v90, v91
	v_lshl_add_u64 v[98:99], v[98:99], 1, s[10:11]
	v_add_f32_e32 v88, v92, v89
	v_mul_f32_e32 v89, v91, v91
	global_store_dwordx4 v[98:99], v[100:103], off
	v_fmac_f32_e32 v89, v90, v90
	s_nop 0
	v_add_f32_e32 v100, v89, v88
	s_nop 1
	s_nop 1
	v_pk_add_f32 v[82:83], v[82:83], v[246:247]
	v_pk_add_f32 v[86:87], v[86:87], v[242:243]
	v_pk_add_f32 v[84:85], v[84:85], v[240:241]
	v_pk_add_f32 v[80:81], v[80:81], v[244:245]
	global_store_dwordx4 v[96:97], v[84:87], off offset:512
	global_store_dwordx4 v[96:97], v[80:83], off offset:528
	v_cvt_pk_bf16_f32 v91, v82, v83
	v_cvt_pk_bf16_f32 v88, v84, v85
	v_mul_f32_e32 v83, v83, v83
	v_fmac_f32_e32 v83, v82, v82
	v_mul_f32_e32 v82, v85, v85
	v_fmac_f32_e32 v82, v84, v84
	v_mul_f32_e32 v84, v87, v87
	v_cvt_pk_bf16_f32 v90, v80, v81
	v_fmac_f32_e32 v84, v86, v86
	v_mul_f32_e32 v81, v81, v81
	v_add_f32_e32 v82, v82, v84
	v_fmac_f32_e32 v81, v80, v80
	v_add_f32_e32 v80, v82, v81
	v_add_f32_e32 v80, v83, v80
	v_add_f32_e32 v80, v100, v80
	ds_bpermute_b32 v81, v180, v80
	v_cvt_pk_bf16_f32 v89, v86, v87
	global_store_dwordx4 v[98:99], v[88:91], off offset:256
	s_waitcnt lgkmcnt(0)
	v_add_f32_e32 v80, v80, v81
	ds_bpermute_b32 v81, v181, v80
	s_and_saveexec_b64 s[24:25], s[6:7]
	s_cbranch_execz .LBB0_743
	s_waitcnt lgkmcnt(0)
	v_add_f32_e32 v80, v80, v81
	v_fma_f32 v80, v80, s65, 0.5
	v_trunc_f32_e32 v80, v80
	v_mul_f32_e32 v81, 0x2f800000, v80
	v_floor_f32_e32 v81, v81
	v_fmac_f32_e32 v80, 0xcf800000, v81
	v_cvt_u32_f32_e32 v80, v80
	v_cvt_u32_f32_e32 v81, v81
	v_lshl_add_u64 v[82:83], v[138:139], 3, s[14:15]
	global_atomic_add_x2 v[82:83], v[80:81], off offset:256

.LBB0_744:
	v_or_b32_e32 v80, 48, v138
	s_waitcnt lgkmcnt(0)
	v_ashrrev_i32_e32 v81, 31, v80
	v_lshlrev_b64 v[80:81], 10, v[80:81]
	v_lshl_add_u64 v[82:83], v[80:81], 0, v[142:143]
	v_lshl_add_u64 v[80:81], v[82:83], 2, s[12:13]
	s_mov_b64 s[98:99], 0x90000
	v_lshl_add_u64 v[250:251], v[248:249], 0, s[98:99]
	global_load_dwordx4 v[232:235], v[250:251], off
	global_load_dwordx4 v[236:239], v[250:251], off offset:16
	global_load_dwordx4 v[240:243], v[250:251], off offset:512
	global_load_dwordx4 v[244:247], v[250:251], off offset:528
	s_waitcnt vmcnt(16)
	s_nop 1
	s_nop 1
	s_mov_b64 s[24:25], -1
	s_and_b64 vcc, exec, s[4:5]
	v_pk_add_f32 v[78:79], v[78:79], v[202:203]
	v_pk_add_f32 v[76:77], v[76:77], v[200:201]
	v_pk_add_f32 v[74:75], v[74:75], v[206:207]
	v_pk_add_f32 v[72:73], v[72:73], v[204:205]
	global_store_dwordx4 v[80:81], v[76:79], off
	global_store_dwordx4 v[80:81], v[72:75], off offset:16
	s_cbranch_vccz .LBB0_746
	s_nop 1
	s_nop 1
	s_mov_b64 s[24:25], 0
	v_pk_add_f32 v[86:87], v[70:71], v[210:211]
	v_pk_add_f32 v[84:85], v[68:69], v[208:209]
	v_pk_add_f32 v[90:91], v[66:67], v[214:215]
	v_pk_add_f32 v[88:89], v[64:65], v[212:213]
	global_store_dwordx4 v[80:81], v[84:87], off offset:512
	global_store_dwordx4 v[80:81], v[88:91], off offset:528
.LBB0_746:
	s_andn2_b64 vcc, exec, s[24:25]
	s_cbranch_vccnz .LBB0_750
	v_cvt_pk_bf16_f32 v84, v76, v77
	v_mul_f32_e32 v77, v77, v77
	v_fmac_f32_e32 v77, v76, v76
	v_mul_f32_e32 v76, v79, v79
	v_cvt_pk_bf16_f32 v86, v72, v73
	v_fmac_f32_e32 v76, v78, v78
	v_mul_f32_e32 v73, v73, v73
	v_add_f32_e32 v76, v77, v76
	v_fmac_f32_e32 v73, v72, v72
	v_cvt_pk_bf16_f32 v85, v78, v79
	v_cvt_pk_bf16_f32 v87, v74, v75
	v_lshl_add_u64 v[82:83], v[82:83], 1, s[10:11]
	v_add_f32_e32 v72, v76, v73
	v_mul_f32_e32 v73, v75, v75
	global_store_dwordx4 v[82:83], v[84:87], off
	v_fmac_f32_e32 v73, v74, v74
	s_nop 0
	v_add_f32_e32 v84, v73, v72
	s_nop 1
	s_nop 1
	v_pk_add_f32 v[66:67], v[66:67], v[214:215]
	v_pk_add_f32 v[70:71], v[70:71], v[210:211]
	v_pk_add_f32 v[68:69], v[68:69], v[208:209]
	v_pk_add_f32 v[64:65], v[64:65], v[212:213]
	global_store_dwordx4 v[80:81], v[68:71], off offset:512
	global_store_dwordx4 v[80:81], v[64:67], off offset:528
	v_cvt_pk_bf16_f32 v75, v66, v67
	v_cvt_pk_bf16_f32 v72, v68, v69
	v_mul_f32_e32 v67, v67, v67
	v_fmac_f32_e32 v67, v66, v66
	v_mul_f32_e32 v66, v69, v69
	v_fmac_f32_e32 v66, v68, v68
	v_mul_f32_e32 v68, v71, v71
	v_cvt_pk_bf16_f32 v74, v64, v65
	v_fmac_f32_e32 v68, v70, v70
	v_mul_f32_e32 v65, v65, v65
	v_add_f32_e32 v66, v66, v68
	v_fmac_f32_e32 v65, v64, v64
	v_add_f32_e32 v64, v66, v65
	v_add_f32_e32 v64, v67, v64
	v_add_f32_e32 v64, v84, v64
	ds_bpermute_b32 v65, v180, v64
	v_cvt_pk_bf16_f32 v73, v70, v71
	global_store_dwordx4 v[82:83], v[72:75], off offset:256
	s_waitcnt lgkmcnt(0)
	v_add_f32_e32 v64, v64, v65
	ds_bpermute_b32 v65, v181, v64
	s_and_saveexec_b64 s[24:25], s[6:7]
	s_cbranch_execz .LBB0_749
	s_waitcnt lgkmcnt(0)
	v_add_f32_e32 v64, v64, v65
	v_fma_f32 v64, v64, s65, 0.5
	v_trunc_f32_e32 v64, v64
	v_mul_f32_e32 v65, 0x2f800000, v64
	v_floor_f32_e32 v65, v65
	v_fmac_f32_e32 v64, 0xcf800000, v65
	v_cvt_u32_f32_e32 v64, v64
	v_cvt_u32_f32_e32 v65, v65
	v_lshl_add_u64 v[66:67], v[138:139], 3, s[14:15]
	global_atomic_add_x2 v[66:67], v[64:65], off offset:384

.LBB0_750:
	s_mov_b64 s[24:25], 0x20000
	v_lshl_add_u64 v[66:67], v[140:141], 0, s[24:25]
	s_waitcnt lgkmcnt(0)
	v_lshl_add_u64 v[64:65], v[66:67], 2, s[12:13]
	s_mov_b64 s[98:99], 0xa0000
	v_lshl_add_u64 v[250:251], v[248:249], 0, s[98:99]
	global_load_dwordx4 v[200:203], v[250:251], off
	global_load_dwordx4 v[204:207], v[250:251], off offset:16
	global_load_dwordx4 v[208:211], v[250:251], off offset:512
	global_load_dwordx4 v[212:215], v[250:251], off offset:528
	s_waitcnt vmcnt(16)
	s_nop 1
	s_nop 1
	s_mov_b64 s[24:25], -1
	s_and_b64 vcc, exec, s[4:5]
	v_pk_add_f32 v[62:63], v[62:63], v[218:219]
	v_pk_add_f32 v[60:61], v[60:61], v[216:217]
	v_pk_add_f32 v[58:59], v[58:59], v[222:223]
	v_pk_add_f32 v[56:57], v[56:57], v[220:221]
	global_store_dwordx4 v[64:65], v[60:63], off
	global_store_dwordx4 v[64:65], v[56:59], off offset:16
	s_cbranch_vccz .LBB0_752
	s_nop 1
	s_nop 1
	s_mov_b64 s[24:25], 0
	v_pk_add_f32 v[70:71], v[54:55], v[226:227]
	v_pk_add_f32 v[68:69], v[52:53], v[224:225]
	v_pk_add_f32 v[74:75], v[50:51], v[230:231]
	v_pk_add_f32 v[72:73], v[48:49], v[228:229]
	global_store_dwordx4 v[64:65], v[68:71], off offset:512
	global_store_dwordx4 v[64:65], v[72:75], off offset:528
.LBB0_752:
	s_andn2_b64 vcc, exec, s[24:25]
	s_cbranch_vccnz .LBB0_756
	v_cvt_pk_bf16_f32 v68, v60, v61
	v_mul_f32_e32 v61, v61, v61
	v_fmac_f32_e32 v61, v60, v60
	v_mul_f32_e32 v60, v63, v63
	v_cvt_pk_bf16_f32 v70, v56, v57
	v_fmac_f32_e32 v60, v62, v62
	v_mul_f32_e32 v57, v57, v57
	v_add_f32_e32 v60, v61, v60
	v_fmac_f32_e32 v57, v56, v56
	v_cvt_pk_bf16_f32 v69, v62, v63
	v_cvt_pk_bf16_f32 v71, v58, v59
	v_lshl_add_u64 v[66:67], v[66:67], 1, s[10:11]
	v_add_f32_e32 v56, v60, v57
	v_mul_f32_e32 v57, v59, v59
	global_store_dwordx4 v[66:67], v[68:71], off
	v_fmac_f32_e32 v57, v58, v58
	s_nop 0
	v_add_f32_e32 v68, v57, v56
	s_nop 1
	s_nop 1
	v_pk_add_f32 v[50:51], v[50:51], v[230:231]
	v_pk_add_f32 v[54:55], v[54:55], v[226:227]
	v_pk_add_f32 v[52:53], v[52:53], v[224:225]
	v_pk_add_f32 v[48:49], v[48:49], v[228:229]
	global_store_dwordx4 v[64:65], v[52:55], off offset:512
	global_store_dwordx4 v[64:65], v[48:51], off offset:528
	v_cvt_pk_bf16_f32 v59, v50, v51
	v_cvt_pk_bf16_f32 v56, v52, v53
	v_mul_f32_e32 v51, v51, v51
	v_fmac_f32_e32 v51, v50, v50
	v_mul_f32_e32 v50, v53, v53
	v_fmac_f32_e32 v50, v52, v52
	v_mul_f32_e32 v52, v55, v55
	v_cvt_pk_bf16_f32 v58, v48, v49
	v_fmac_f32_e32 v52, v54, v54
	v_mul_f32_e32 v49, v49, v49
	v_add_f32_e32 v50, v50, v52
	v_fmac_f32_e32 v49, v48, v48
	v_add_f32_e32 v48, v50, v49
	v_add_f32_e32 v48, v51, v48
	v_add_f32_e32 v48, v68, v48
	ds_bpermute_b32 v49, v180, v48
	v_cvt_pk_bf16_f32 v57, v54, v55
	global_store_dwordx4 v[66:67], v[56:59], off offset:256
	s_waitcnt lgkmcnt(0)
	v_add_f32_e32 v48, v48, v49
	ds_bpermute_b32 v49, v181, v48
	s_and_saveexec_b64 s[24:25], s[6:7]
	s_cbranch_execz .LBB0_755
	s_waitcnt lgkmcnt(0)
	v_add_f32_e32 v48, v48, v49
	v_fma_f32 v48, v48, s65, 0.5
	v_trunc_f32_e32 v48, v48
	v_mul_f32_e32 v49, 0x2f800000, v48
	v_floor_f32_e32 v49, v49
	v_fmac_f32_e32 v48, 0xcf800000, v49
	v_cvt_u32_f32_e32 v48, v48
	v_cvt_u32_f32_e32 v49, v49
	v_lshl_add_u64 v[50:51], v[138:139], 3, s[14:15]
	global_atomic_add_x2 v[50:51], v[48:49], off offset:1024

.LBB0_756:
	s_mov_b64 s[24:25], 0x24000
	v_lshl_add_u64 v[50:51], v[140:141], 0, s[24:25]
	s_waitcnt lgkmcnt(0)
	v_lshl_add_u64 v[48:49], v[50:51], 2, s[12:13]
	s_mov_b64 s[98:99], 0xb0000
	v_lshl_add_u64 v[250:251], v[248:249], 0, s[98:99]
	global_load_dwordx4 v[216:219], v[250:251], off
	global_load_dwordx4 v[220:223], v[250:251], off offset:16
	global_load_dwordx4 v[224:227], v[250:251], off offset:512
	global_load_dwordx4 v[228:231], v[250:251], off offset:528
	s_waitcnt vmcnt(16)
	s_nop 1
	s_nop 1
	s_mov_b64 s[24:25], -1
	s_and_b64 vcc, exec, s[4:5]
	v_pk_add_f32 v[46:47], v[46:47], v[234:235]
	v_pk_add_f32 v[44:45], v[44:45], v[232:233]
	v_pk_add_f32 v[42:43], v[42:43], v[238:239]
	v_pk_add_f32 v[40:41], v[40:41], v[236:237]
	global_store_dwordx4 v[48:49], v[44:47], off
	global_store_dwordx4 v[48:49], v[40:43], off offset:16
	s_cbranch_vccz .LBB0_758
	s_nop 1
	s_nop 1
	s_mov_b64 s[24:25], 0
	v_pk_add_f32 v[54:55], v[38:39], v[242:243]
	v_pk_add_f32 v[52:53], v[36:37], v[240:241]
	v_pk_add_f32 v[58:59], v[34:35], v[246:247]
	v_pk_add_f32 v[56:57], v[32:33], v[244:245]
	global_store_dwordx4 v[48:49], v[52:55], off offset:512
	global_store_dwordx4 v[48:49], v[56:59], off offset:528
.LBB0_758:
	s_andn2_b64 vcc, exec, s[24:25]
	s_cbranch_vccnz .LBB0_762
	v_cvt_pk_bf16_f32 v52, v44, v45
	v_mul_f32_e32 v45, v45, v45
	v_fmac_f32_e32 v45, v44, v44
	v_mul_f32_e32 v44, v47, v47
	v_cvt_pk_bf16_f32 v54, v40, v41
	v_fmac_f32_e32 v44, v46, v46
	v_mul_f32_e32 v41, v41, v41
	v_add_f32_e32 v44, v45, v44
	v_fmac_f32_e32 v41, v40, v40
	v_cvt_pk_bf16_f32 v53, v46, v47
	v_cvt_pk_bf16_f32 v55, v42, v43
	v_lshl_add_u64 v[50:51], v[50:51], 1, s[10:11]
	v_add_f32_e32 v40, v44, v41
	v_mul_f32_e32 v41, v43, v43
	global_store_dwordx4 v[50:51], v[52:55], off
	v_fmac_f32_e32 v41, v42, v42
	s_nop 0
	v_add_f32_e32 v52, v41, v40
	s_nop 1
	s_nop 1
	v_pk_add_f32 v[34:35], v[34:35], v[246:247]
	v_pk_add_f32 v[38:39], v[38:39], v[242:243]
	v_pk_add_f32 v[36:37], v[36:37], v[240:241]
	v_pk_add_f32 v[32:33], v[32:33], v[244:245]
	global_store_dwordx4 v[48:49], v[36:39], off offset:512
	global_store_dwordx4 v[48:49], v[32:35], off offset:528
	v_cvt_pk_bf16_f32 v43, v34, v35
	v_cvt_pk_bf16_f32 v40, v36, v37
	v_mul_f32_e32 v35, v35, v35
	v_fmac_f32_e32 v35, v34, v34
	v_mul_f32_e32 v34, v37, v37
	v_fmac_f32_e32 v34, v36, v36
	v_mul_f32_e32 v36, v39, v39
	v_cvt_pk_bf16_f32 v42, v32, v33
	v_fmac_f32_e32 v36, v38, v38
	v_mul_f32_e32 v33, v33, v33
	v_add_f32_e32 v34, v34, v36
	v_fmac_f32_e32 v33, v32, v32
	v_add_f32_e32 v32, v34, v33
	v_add_f32_e32 v32, v35, v32
	v_add_f32_e32 v32, v52, v32
	ds_bpermute_b32 v33, v180, v32
	v_cvt_pk_bf16_f32 v41, v38, v39
	global_store_dwordx4 v[50:51], v[40:43], off offset:256
	s_waitcnt lgkmcnt(0)
	v_add_f32_e32 v32, v32, v33
	ds_bpermute_b32 v33, v181, v32
	s_and_saveexec_b64 s[24:25], s[6:7]
	s_cbranch_execz .LBB0_761
	s_waitcnt lgkmcnt(0)
	v_add_f32_e32 v32, v32, v33
	v_fma_f32 v32, v32, s65, 0.5
	v_trunc_f32_e32 v32, v32
	v_mul_f32_e32 v33, 0x2f800000, v32
	v_floor_f32_e32 v33, v33
	v_fmac_f32_e32 v32, 0xcf800000, v33
	v_cvt_u32_f32_e32 v32, v32
	v_cvt_u32_f32_e32 v33, v33
	v_lshl_add_u64 v[34:35], v[138:139], 3, s[14:15]
	global_atomic_add_x2 v[34:35], v[32:33], off offset:1152

.LBB0_762:
	s_mov_b64 s[24:25], 0x28000
	v_lshl_add_u64 v[34:35], v[140:141], 0, s[24:25]
	s_waitcnt lgkmcnt(0)
	v_lshl_add_u64 v[32:33], v[34:35], 2, s[12:13]
	s_waitcnt vmcnt(12)
	s_nop 1
	s_nop 1
	s_mov_b64 s[24:25], -1
	s_and_b64 vcc, exec, s[4:5]
	v_pk_add_f32 v[30:31], v[30:31], v[202:203]
	v_pk_add_f32 v[28:29], v[28:29], v[200:201]
	v_pk_add_f32 v[26:27], v[26:27], v[206:207]
	v_pk_add_f32 v[24:25], v[24:25], v[204:205]
	global_store_dwordx4 v[32:33], v[28:31], off
	global_store_dwordx4 v[32:33], v[24:27], off offset:16
	s_cbranch_vccz .LBB0_764
	s_nop 1
	s_nop 1
	s_mov_b64 s[24:25], 0
	v_pk_add_f32 v[38:39], v[22:23], v[210:211]
	v_pk_add_f32 v[36:37], v[20:21], v[208:209]
	v_pk_add_f32 v[42:43], v[18:19], v[214:215]
	v_pk_add_f32 v[40:41], v[16:17], v[212:213]
	global_store_dwordx4 v[32:33], v[36:39], off offset:512
	global_store_dwordx4 v[32:33], v[40:43], off offset:528
.LBB0_764:
	s_andn2_b64 vcc, exec, s[24:25]
	s_cbranch_vccnz .LBB0_768
	v_cvt_pk_bf16_f32 v36, v28, v29
	v_mul_f32_e32 v29, v29, v29
	v_fmac_f32_e32 v29, v28, v28
	v_mul_f32_e32 v28, v31, v31
	v_cvt_pk_bf16_f32 v38, v24, v25
	v_fmac_f32_e32 v28, v30, v30
	v_mul_f32_e32 v25, v25, v25
	v_add_f32_e32 v28, v29, v28
	v_fmac_f32_e32 v25, v24, v24
	v_cvt_pk_bf16_f32 v37, v30, v31
	v_cvt_pk_bf16_f32 v39, v26, v27
	v_lshl_add_u64 v[34:35], v[34:35], 1, s[10:11]
	v_add_f32_e32 v24, v28, v25
	v_mul_f32_e32 v25, v27, v27
	global_store_dwordx4 v[34:35], v[36:39], off
	v_fmac_f32_e32 v25, v26, v26
	s_nop 0
	v_add_f32_e32 v36, v25, v24
	s_nop 1
	s_nop 1
	v_pk_add_f32 v[18:19], v[18:19], v[214:215]
	v_pk_add_f32 v[22:23], v[22:23], v[210:211]
	v_pk_add_f32 v[20:21], v[20:21], v[208:209]
	v_pk_add_f32 v[16:17], v[16:17], v[212:213]
	global_store_dwordx4 v[32:33], v[20:23], off offset:512
	global_store_dwordx4 v[32:33], v[16:19], off offset:528
	v_cvt_pk_bf16_f32 v27, v18, v19
	v_cvt_pk_bf16_f32 v24, v20, v21
	v_mul_f32_e32 v19, v19, v19
	v_fmac_f32_e32 v19, v18, v18
	v_mul_f32_e32 v18, v21, v21
	v_fmac_f32_e32 v18, v20, v20
	v_mul_f32_e32 v20, v23, v23
	v_cvt_pk_bf16_f32 v26, v16, v17
	v_fmac_f32_e32 v20, v22, v22
	v_mul_f32_e32 v17, v17, v17
	v_add_f32_e32 v18, v18, v20
	v_fmac_f32_e32 v17, v16, v16
	v_add_f32_e32 v16, v18, v17
	v_add_f32_e32 v16, v19, v16
	v_add_f32_e32 v16, v36, v16
	ds_bpermute_b32 v17, v180, v16
	v_cvt_pk_bf16_f32 v25, v22, v23
	global_store_dwordx4 v[34:35], v[24:27], off offset:256
	s_waitcnt lgkmcnt(0)
	v_add_f32_e32 v16, v16, v17
	ds_bpermute_b32 v17, v181, v16
	s_and_saveexec_b64 s[24:25], s[6:7]
	s_cbranch_execz .LBB0_767
	s_waitcnt lgkmcnt(0)
	v_add_f32_e32 v16, v16, v17
	v_fma_f32 v16, v16, s65, 0.5
	v_trunc_f32_e32 v16, v16
	v_mul_f32_e32 v17, 0x2f800000, v16
	v_floor_f32_e32 v17, v17
	v_fmac_f32_e32 v16, 0xcf800000, v17
	v_cvt_u32_f32_e32 v16, v16
	v_cvt_u32_f32_e32 v17, v17
	v_lshl_add_u64 v[18:19], v[138:139], 3, s[14:15]
	global_atomic_add_x2 v[18:19], v[16:17], off offset:1280

.LBB0_768:
	s_mov_b64 s[24:25], 0x2c000
	v_lshl_add_u64 v[18:19], v[140:141], 0, s[24:25]
	s_waitcnt lgkmcnt(0)
	v_lshl_add_u64 v[16:17], v[18:19], 2, s[12:13]
	s_waitcnt vmcnt(8)
	s_nop 1
	s_nop 1
	s_mov_b64 s[24:25], -1
	s_and_b64 vcc, exec, s[4:5]
	v_pk_add_f32 v[14:15], v[14:15], v[218:219]
	v_pk_add_f32 v[12:13], v[12:13], v[216:217]
	v_pk_add_f32 v[10:11], v[10:11], v[222:223]
	v_pk_add_f32 v[8:9], v[8:9], v[220:221]
	global_store_dwordx4 v[16:17], v[12:15], off
	global_store_dwordx4 v[16:17], v[8:11], off offset:16
	s_cbranch_vccz .LBB0_770
	s_nop 1
	s_nop 1
	s_mov_b64 s[24:25], 0
	v_pk_add_f32 v[22:23], v[6:7], v[226:227]
	v_pk_add_f32 v[20:21], v[4:5], v[224:225]
	v_pk_add_f32 v[26:27], v[2:3], v[230:231]
	v_pk_add_f32 v[24:25], v[0:1], v[228:229]
	global_store_dwordx4 v[16:17], v[20:23], off offset:512
	global_store_dwordx4 v[16:17], v[24:27], off offset:528
.LBB0_770:
	s_andn2_b64 vcc, exec, s[24:25]
	s_cbranch_vccnz .LBB0_717
	v_cvt_pk_bf16_f32 v20, v12, v13
	v_mul_f32_e32 v13, v13, v13
	v_fmac_f32_e32 v13, v12, v12
	v_mul_f32_e32 v12, v15, v15
	v_cvt_pk_bf16_f32 v22, v8, v9
	v_fmac_f32_e32 v12, v14, v14
	v_mul_f32_e32 v9, v9, v9
	v_add_f32_e32 v12, v13, v12
	v_fmac_f32_e32 v9, v8, v8
	v_cvt_pk_bf16_f32 v21, v14, v15
	v_cvt_pk_bf16_f32 v23, v10, v11
	v_lshl_add_u64 v[18:19], v[18:19], 1, s[10:11]
	v_add_f32_e32 v8, v12, v9
	v_mul_f32_e32 v9, v11, v11
	global_store_dwordx4 v[18:19], v[20:23], off
	v_fmac_f32_e32 v9, v10, v10
	s_nop 0
	v_add_f32_e32 v20, v9, v8
	s_nop 1
	s_nop 1
	v_pk_add_f32 v[2:3], v[2:3], v[230:231]
	v_pk_add_f32 v[6:7], v[6:7], v[226:227]
	v_pk_add_f32 v[4:5], v[4:5], v[224:225]
	v_pk_add_f32 v[0:1], v[0:1], v[228:229]
	global_store_dwordx4 v[16:17], v[4:7], off offset:512
	global_store_dwordx4 v[16:17], v[0:3], off offset:528
	v_cvt_pk_bf16_f32 v11, v2, v3
	v_cvt_pk_bf16_f32 v8, v4, v5
	v_mul_f32_e32 v3, v3, v3
	v_fmac_f32_e32 v3, v2, v2
	v_mul_f32_e32 v2, v5, v5
	v_fmac_f32_e32 v2, v4, v4
	v_mul_f32_e32 v4, v7, v7
	v_cvt_pk_bf16_f32 v10, v0, v1
	v_fmac_f32_e32 v4, v6, v6
	v_mul_f32_e32 v1, v1, v1
	v_add_f32_e32 v2, v2, v4
	v_fmac_f32_e32 v1, v0, v0
	v_add_f32_e32 v0, v2, v1
	v_add_f32_e32 v0, v3, v0
	v_add_f32_e32 v0, v20, v0
	ds_bpermute_b32 v1, v180, v0
	v_cvt_pk_bf16_f32 v9, v6, v7
	global_store_dwordx4 v[18:19], v[8:11], off offset:256
	s_waitcnt lgkmcnt(0)
	v_add_f32_e32 v0, v0, v1
	ds_bpermute_b32 v1, v181, v0
	s_and_saveexec_b64 s[24:25], s[6:7]
	s_cbranch_execz .LBB0_716
	s_waitcnt lgkmcnt(0)
	v_add_f32_e32 v0, v0, v1
	v_fma_f32 v0, v0, s65, 0.5
	v_trunc_f32_e32 v0, v0
	v_mul_f32_e32 v1, 0x2f800000, v0
	v_floor_f32_e32 v1, v1
	v_fmac_f32_e32 v0, 0xcf800000, v1
	v_cvt_u32_f32_e32 v0, v0
	v_cvt_u32_f32_e32 v1, v1
	v_lshl_add_u64 v[2:3], v[138:139], 3, s[14:15]
	global_atomic_add_x2 v[2:3], v[0:1], off offset:1408
	s_branch .LBB0_716
